# output stores (final y, k/v f32 outputs, DeltaNet z) issued as plain instead of nontemporal stores
# baseline (speedup 1.0000x reference)
; template <bool FINAL>
; DI void norm_rows(const Params& p, const float* gain, int in_mode  , int npart  , int pool_j  , int gw, int NGW, int lane) {
;     ...
; #pragma unroll
;         for (int j = 0; j < 4; ++j) { s += (v[j].x * v[j].x + v[j].y * v[j].y) + (v[j].z * v[j].z + v[j].w * v[j].w); }
;         const float rstd = rsqrtf(wave_sum(s) * (1.f / D) + EPS);
; #pragma unroll
;         for (int j = 0; j < 4; ++j) v[j] = v[j] * rstd * gv[j];
;         if (FINAL) {
; #pragma unroll
;             for (int j = 0; j < 4; ++j) __builtin_nontemporal_store(v[j], (f32x4*)(X + (size_t)row * D + 4 * lane + 256 * j));
.LBB0_61:
	s_waitcnt vmcnt(0) lgkmcnt(0)
	v_pk_mul_f32 v[36:37], v[26:27], v[26:27]
	v_pk_mul_f32 v[38:39], v[24:25], v[24:25]
	v_pk_mul_f32 v[32:33], v[22:23], v[22:23]
	v_pk_mul_f32 v[34:35], v[20:21], v[20:21]
	v_pk_mov_b32 v[40:41], v[38:39], v[36:37] op_sel:[1,0]
	v_mov_b32_e32 v39, v37
	v_pk_add_f32 v[36:37], v[40:41], v[38:39]
	v_pk_mov_b32 v[38:39], v[34:35], v[32:33] op_sel:[1,0]
	v_mov_b32_e32 v35, v33
	v_pk_add_f32 v[32:33], v[38:39], v[34:35]
	v_pk_add_f32 v[36:37], v[36:37], v[36:37] op_sel_hi:[0,1]
	v_pk_add_f32 v[32:33], v[32:33], v[32:33] op_sel_hi:[0,1]
	v_mul_f32_e32 v32, v16, v16
	v_pk_fma_f32 v[34:35], v[16:17], v[16:17], v[32:33] op_sel_hi:[1,1,0]
	v_mul_f32_e32 v32, v18, v18
	v_pk_fma_f32 v[38:39], v[18:19], v[18:19], v[32:33] op_sel_hi:[1,1,0]
	v_mul_f32_e32 v34, v28, v28
	v_mul_f32_e32 v38, v29, v29
	v_mul_f32_e32 v36, v30, v30
	v_mul_f32_e32 v32, v31, v31
	v_pk_add_f32 v[34:35], v[34:35], v[38:39]
	v_pk_add_f32 v[32:33], v[36:37], v[32:33]
	s_add_u32 s0, s0, s20
	v_pk_add_f32 v[32:33], v[34:35], v[32:33]
	s_addc_u32 s1, s1, s21
	v_add_f32_e32 v32, v32, v33
	ds_bpermute_b32 v33, v88, v32
	s_cmp_lt_i32 s0, 0x8200
	s_waitcnt lgkmcnt(0)
	v_add_f32_e32 v32, v32, v33
	ds_bpermute_b32 v33, v89, v32
	s_waitcnt lgkmcnt(0)
	v_add_f32_e32 v32, v32, v33
	ds_bpermute_b32 v33, v90, v32
	s_waitcnt lgkmcnt(0)
	v_add_f32_e32 v32, v32, v33
	ds_bpermute_b32 v33, v91, v32
	s_waitcnt lgkmcnt(0)
	v_add_f32_e32 v32, v32, v33
	ds_bpermute_b32 v33, v92, v32
	s_waitcnt lgkmcnt(0)
	v_add_f32_e32 v32, v32, v33
	ds_bpermute_b32 v33, v93, v32
	s_waitcnt lgkmcnt(0)
	v_add_f32_e32 v32, v32, v33
	v_fmamk_f32 v32, v32, 0x3a800000, v217
	v_mul_f32_e32 v33, 0x4b800000, v32
	v_cmp_gt_f32_e32 vcc, s87, v32
	s_nop 1
	v_cndmask_b32_e32 v32, v32, v33, vcc
	v_rsq_f32_e32 v32, v32
	s_nop 0
	v_mul_f32_e32 v33, 0x45800000, v32
	v_cndmask_b32_e32 v32, v32, v33, vcc
	v_pk_mul_f32 v[24:25], v[24:25], v[32:33] op_sel_hi:[1,0]
	v_pk_mul_f32 v[26:27], v[26:27], v[32:33] op_sel_hi:[1,0]
	v_pk_mul_f32 v[20:21], v[20:21], v[32:33] op_sel_hi:[1,0]
	v_pk_mul_f32 v[22:23], v[22:23], v[32:33] op_sel_hi:[1,0]
	v_pk_mul_f32 v[34:35], v[16:17], v[32:33] op_sel_hi:[1,0]
	v_pk_mul_f32 v[36:37], v[18:19], v[32:33] op_sel_hi:[1,0]
	v_pk_mul_f32 v[18:19], v[2:3], v[26:27]
	v_pk_mul_f32 v[16:17], v[0:1], v[24:25]
	v_pk_mul_f32 v[28:29], v[28:29], v[32:33] op_sel_hi:[1,0]
	v_pk_mul_f32 v[30:31], v[30:31], v[32:33] op_sel_hi:[1,0]
	v_pk_mul_f32 v[22:23], v[6:7], v[22:23]
	v_pk_mul_f32 v[20:21], v[4:5], v[20:21]
	v_pk_mul_f32 v[26:27], v[10:11], v[36:37]
	v_pk_mul_f32 v[24:25], v[8:9], v[34:35]
	v_pk_mul_f32 v[30:31], v[14:15], v[30:31]
	v_pk_mul_f32 v[28:29], v[12:13], v[28:29]
	global_store_dwordx4 v[52:53], v[16:19], off
	global_store_dwordx4 v[52:53], v[20:23], off offset:1024
	global_store_dwordx4 v[52:53], v[24:27], off offset:2048
	global_store_dwordx4 v[52:53], v[28:31], off offset:3072
	v_lshl_add_u64 v[52:53], v[52:53], 0, s[10:11]
	s_cbranch_scc0 .LBB0_67

; #define LAS __attribute__((address_space(3)))
;     DI void operator()(const f32x4 (&acc)[2][2][4][2], const Unit& u, int wr, int wc, int fr, int fq) const {
;     ...
;                 const int row = u.pm * 256 + ai * 128 + wr * 64 + m * 16 + fr;
;                 int s, b, t; rowinfo(row, s, b, t);
; #pragma unroll
;                 for (int bj = 0; bj < 2; ++bj) {
;                     const int col = u.pn * 256 + bj * 128 + wc * 32 + 8 * fq;
;                     u32x4 w; w.x = pk2(acc[ai][bj][m][0][0], acc[ai][bj][m][0][1]); w.y = pk2(acc[ai][bj][m][0][2], acc[ai][bj][m][0][3]); w.z = pk2(acc[ai][bj][m][1][0], acc[ai][bj][m][1][1]); w.w = pk2(acc[ai][bj][m][1][2], acc[ai][bj][m][1][3]);
;                     if (u.pn < 4) { *(u32x4*)(Q + (size_t)row * D + col) = w; }
;                     else if (u.pn < 8) {
;                         const int c = col - D;
;                         float* o = out + (s ? O_KS + (size_t)(row - MP) * D : O_KP + (size_t)row * D) + c; __builtin_nontemporal_store(acc[ai][bj][m][0], (f32x4*)o); __builtin_nontemporal_store(acc[ai][bj][m][1], (f32x4*)(o + 4));
;                         bf16_t* kb = s ? KS + ((size_t)b * LK + PAST + t) * D + c : KP + (size_t)row * D + c; *(u32x4*)kb = w;
;                     } else {
;                         const int c = col - 2 * D;
;                         float* o = out + (s ? O_VS + (size_t)(row - MP) * D : O_VP + (size_t)row * D) + c; __builtin_nontemporal_store(acc[ai][bj][m][0], (f32x4*)o); __builtin_nontemporal_store(acc[ai][bj][m][1], (f32x4*)(o + 4));
;                         LAS bf16_t* tp = (LAS bf16_t*)tw + (8 * fq) * 16 + fr;
;                         tp[0] = (bf16_t)(w.x & 0xffff); tp[16] = (bf16_t)(w.x >> 16); tp[32] = (bf16_t)(w.y & 0xffff); tp[48] = (bf16_t)(w.y >> 16);
;                         tp[64] = (bf16_t)(w.z & 0xffff); tp[80] = (bf16_t)(w.z >> 16); tp[96] = (bf16_t)(w.w & 0xffff); tp[112] = (bf16_t)(w.w >> 16);
;                         asm volatile("s_waitcnt lgkmcnt(0)" ::: "memory");
;                         const u32x4 tv = *(const LAS u32x4*)(tw + (lane >> 1) * 32 + (lane & 1) * 16);
;                         asm volatile("s_waitcnt lgkmcnt(0)" ::: "memory");
;                         const int cc = (col - 8 * fq) - 2 * D + (lane >> 1), h = cc >> 6, d = cc & 63, t0 = (t - fr) + (lane & 1) * 8;
.LBB0_368:
	s_lshl_b32 s30, s26, 8
	s_lshl_b32 s1, s0, 8
	s_add_i32 s30, s30, s34
	s_or_b32 s26, s1, s35
	s_cmp_gt_i32 s0, 3
	s_cselect_b64 s[4:5], -1, 0
	s_cmp_gt_u32 s0, 7
	v_or_b32_e32 v156, s30, v147
	s_movk_i32 s0, 0x7fff
	s_cselect_b64 s[6:7], -1, 0
	s_ashr_i32 s31, s30, 12
	v_cmp_lt_i32_e64 s[42:43], s0, v156
	v_add_u32_e32 v130, 0xffff8000, v156
	v_cmp_gt_i32_e64 s[0:1], s81, v156
	v_lshrrev_b32_e32 v64, 6, v130
	v_mov_b32_e32 v132, s31
	v_cndmask_b32_e64 v131, 15, v234, s[0:1]
	v_cndmask_b32_e64 v134, v64, v132, s[0:1]
	v_bitop3_b32 v64, v131, s30, v147 bitop3:0xe0
	v_ashrrev_i32_e32 v131, 31, v130
	v_lshlrev_b64 v[130:131], 10, v[130:131]
	v_ashrrev_i32_e32 v157, 31, v156
	v_add_u32_e32 v166, v64, v179
	v_add_u32_e32 v64, 0x800, v64
	v_lshl_add_u64 v[168:169], v[130:131], 0, s[70:71]
	v_lshlrev_b64 v[132:133], 10, v[156:157]
	v_lshl_add_u64 v[162:163], v[130:131], 0, s[74:75]
	v_mad_i64_i32 v[130:131], s[10:11], v134, s22, v[64:65]
	v_lshl_add_u64 v[170:171], v[132:133], 0, s[72:73]
	v_lshlrev_b32_e32 v183, 4, v134
	v_ashrrev_i32_e32 v167, 31, v166
	v_lshl_add_u64 v[164:165], v[132:133], 0, s[76:77]
	v_lshlrev_b64 v[158:159], 11, v[130:131]
	v_lshlrev_b64 v[160:161], 11, v[156:157]
	v_or_b32_e32 v154, s26, v176
	v_cvt_pk_bf16_f32 v130, v126, v127
	v_cvt_pk_bf16_f32 v131, v128, v129
	v_cvt_pk_bf16_f32 v132, v122, v123
	v_cvt_pk_bf16_f32 v133, v124, v125
	s_mov_b64 s[10:11], -1
	s_and_b64 vcc, exec, s[4:5]
	s_cbranch_vccz .LBB0_378
	s_and_b64 vcc, exec, s[6:7]
	s_cbranch_vccz .LBB0_375
	v_cndmask_b32_e64 v135, v169, v171, s[0:1]
	v_cndmask_b32_e64 v134, v168, v170, s[0:1]
	v_lshl_add_u64 v[134:135], v[134:135], 2, s[28:29]
	v_mov_b32_e32 v155, v65
	v_lshl_add_u64 v[134:135], v[154:155], 2, v[134:135]
	v_add_co_u32_e32 v136, vcc, 0xffffe000, v134
	v_add_u32_e32 v64, v181, v178
	s_nop 0
	v_addc_co_u32_e32 v137, vcc, -1, v135, vcc
	v_add_co_u32_e32 v134, vcc, 0xffffe010, v134
	global_store_dwordx4 v[136:137], v[126:129], off
	s_nop 0
	v_addc_co_u32_e32 v135, vcc, -1, v135, vcc
	global_store_dwordx4 v[134:135], v[122:125], off
	ds_write_b16 v180, v130
	ds_write_b16_d16_hi v180, v130 offset:32
	ds_write_b16 v180, v131 offset:64
	ds_write_b16_d16_hi v180, v131 offset:96
	ds_write_b16 v180, v132 offset:128
	ds_write_b16_d16_hi v180, v132 offset:160
	ds_write_b16 v180, v133 offset:192
	ds_write_b16_d16_hi v180, v133 offset:224
	s_waitcnt lgkmcnt(0)
	ds_read_b128 v[134:137], v64
	s_add_i32 s10, s26, 0xfffff800
	s_waitcnt lgkmcnt(0)
	s_ashr_i32 s10, s10, 6
	v_add_u32_e32 v174, s10, v183
	v_ashrrev_i32_e32 v175, 31, v174
	s_and_saveexec_b64 s[10:11], s[42:43]
	s_xor_b64 s[10:11], exec, s[10:11]
	v_lshlrev_b64 v[172:173], 6, v[174:175]
	v_or_b32_e32 v64, v172, v146
	v_mov_b64_e32 v[174:175], s[52:53]
	s_movk_i32 s40, 0x1080
	v_mad_u64_u32 v[174:175], s[38:39], v64, s40, v[174:175]
	v_mad_i32_i24 v175, v173, s40, v175
	v_lshl_add_u64 v[172:173], v[174:175], 0, s[96:97]
	s_andn2_saveexec_b64 s[10:11], s[10:11]
	v_lshlrev_b64 v[172:173], 19, v[174:175]
	v_lshl_add_u64 v[172:173], v[148:149], 0, v[172:173]
	s_or_b64 exec, exec, s[10:11]
	v_lshl_add_u64 v[172:173], v[166:167], 1, v[172:173]
	s_waitcnt lgkmcnt(0)
	global_store_dwordx4 v[172:173], v[134:137], off
	s_mov_b64 s[10:11], 0
.LBB0_375:
	s_and_b64 vcc, exec, s[10:11]
	s_cbranch_vccz .LBB0_377
	v_add_u32_e32 v134, 0xfffffc00, v154
	v_cndmask_b32_e64 v137, v163, v165, s[0:1]
	v_cndmask_b32_e64 v136, v162, v164, s[0:1]
	v_lshl_add_u64 v[136:137], v[136:137], 2, s[28:29]
	v_ashrrev_i32_e32 v135, 31, v134
	v_lshl_add_u64 v[136:137], v[134:135], 2, v[136:137]
	global_store_dwordx4 v[136:137], v[126:129], off
	global_store_dwordx4 v[136:137], v[122:125], off offset:16
	s_nop 1
	v_lshl_add_u64 v[122:123], s[50:51], 0, v[158:159]
	v_lshl_add_u64 v[124:125], s[48:49], 0, v[160:161]
	v_cndmask_b32_e64 v123, v123, v125, s[0:1]
	v_cndmask_b32_e64 v122, v122, v124, s[0:1]
	v_lshl_add_u64 v[122:123], v[134:135], 1, v[122:123]
	global_store_dwordx4 v[122:123], v[130:133], off

; #define LAS __attribute__((address_space(3)))
;     DI void operator()(const f32x4 (&acc)[2][2][4][2], const Unit& u, int wr, int wc, int fr, int fq) const {
;     ...
;                 const int row = u.pm * 256 + ai * 128 + wr * 64 + m * 16 + fr;
;                 int s, b, t; rowinfo(row, s, b, t);
; #pragma unroll
;                 for (int bj = 0; bj < 2; ++bj) {
;                     const int col = u.pn * 256 + bj * 128 + wc * 32 + 8 * fq;
;                     u32x4 w; w.x = pk2(acc[ai][bj][m][0][0], acc[ai][bj][m][0][1]); w.y = pk2(acc[ai][bj][m][0][2], acc[ai][bj][m][0][3]); w.z = pk2(acc[ai][bj][m][1][0], acc[ai][bj][m][1][1]); w.w = pk2(acc[ai][bj][m][1][2], acc[ai][bj][m][1][3]);
;                     if (u.pn < 4) { *(u32x4*)(Q + (size_t)row * D + col) = w; }
;                     else if (u.pn < 8) {
;                         const int c = col - D;
;                         float* o = out + (s ? O_KS + (size_t)(row - MP) * D : O_KP + (size_t)row * D) + c; __builtin_nontemporal_store(acc[ai][bj][m][0], (f32x4*)o); __builtin_nontemporal_store(acc[ai][bj][m][1], (f32x4*)(o + 4));
;                         bf16_t* kb = s ? KS + ((size_t)b * LK + PAST + t) * D + c : KP + (size_t)row * D + c; *(u32x4*)kb = w;
;                     } else {
;                         const int c = col - 2 * D;
;                         float* o = out + (s ? O_VS + (size_t)(row - MP) * D : O_VP + (size_t)row * D) + c; __builtin_nontemporal_store(acc[ai][bj][m][0], (f32x4*)o); __builtin_nontemporal_store(acc[ai][bj][m][1], (f32x4*)(o + 4));
;                         LAS bf16_t* tp = (LAS bf16_t*)tw + (8 * fq) * 16 + fr;
;                         tp[0] = (bf16_t)(w.x & 0xffff); tp[16] = (bf16_t)(w.x >> 16); tp[32] = (bf16_t)(w.y & 0xffff); tp[48] = (bf16_t)(w.y >> 16);
;                         tp[64] = (bf16_t)(w.z & 0xffff); tp[80] = (bf16_t)(w.z >> 16); tp[96] = (bf16_t)(w.w & 0xffff); tp[112] = (bf16_t)(w.w >> 16);
;                         asm volatile("s_waitcnt lgkmcnt(0)" ::: "memory");
;                         const u32x4 tv = *(const LAS u32x4*)(tw + (lane >> 1) * 32 + (lane & 1) * 16);
;                         asm volatile("s_waitcnt lgkmcnt(0)" ::: "memory");
;                         const int cc = (col - 8 * fq) - 2 * D + (lane >> 1), h = cc >> 6, d = cc & 63, t0 = (t - fr) + (lane & 1) * 8;
.LBB0_380:
	v_cndmask_b32_e64 v64, 0, 1, s[4:5]
	v_cmp_ne_u32_e64 s[40:41], 1, v64
	v_cndmask_b32_e64 v64, 0, 1, s[6:7]
	v_cvt_pk_bf16_f32 v122, v118, v119
	v_cvt_pk_bf16_f32 v123, v120, v121
	v_cvt_pk_bf16_f32 v124, v114, v115
	v_cvt_pk_bf16_f32 v125, v116, v117
	s_mov_b64 s[10:11], -1
	s_andn2_b64 vcc, exec, s[4:5]
	v_cmp_ne_u32_e64 s[38:39], 1, v64
	s_cbranch_vccnz .LBB0_390
	s_and_b64 vcc, exec, s[38:39]
	s_mov_b64 s[4:5], -1
	s_cbranch_vccnz .LBB0_387
	v_cndmask_b32_e64 v127, v169, v171, s[0:1]
	v_cndmask_b32_e64 v126, v168, v170, s[0:1]
	v_lshl_add_u64 v[126:127], v[126:127], 2, s[28:29]
	v_mov_b32_e32 v155, v65
	v_lshl_add_u64 v[126:127], v[154:155], 2, v[126:127]
	v_add_co_u32_e32 v128, vcc, 0xffffe200, v126
	v_add_u32_e32 v64, v181, v178
	s_nop 0
	v_addc_co_u32_e32 v129, vcc, -1, v127, vcc
	v_add_co_u32_e32 v126, vcc, 0xffffe210, v126
	global_store_dwordx4 v[128:129], v[118:121], off
	s_nop 0
	v_addc_co_u32_e32 v127, vcc, -1, v127, vcc
	global_store_dwordx4 v[126:127], v[114:117], off
	ds_write_b16 v180, v122
	ds_write_b16_d16_hi v180, v122 offset:32
	ds_write_b16 v180, v123 offset:64
	ds_write_b16_d16_hi v180, v123 offset:96
	ds_write_b16 v180, v124 offset:128
	ds_write_b16_d16_hi v180, v124 offset:160
	ds_write_b16 v180, v125 offset:192
	ds_write_b16_d16_hi v180, v125 offset:224
	s_waitcnt lgkmcnt(0)
	ds_read_b128 v[126:129], v64
	s_add_i32 s4, s26, 0xfffff880
	s_waitcnt lgkmcnt(0)
	s_ashr_i32 s4, s4, 6
	v_add_u32_e32 v132, s4, v183
	v_ashrrev_i32_e32 v133, 31, v132
	s_and_saveexec_b64 s[4:5], s[42:43]
	s_xor_b64 s[4:5], exec, s[4:5]
	v_lshlrev_b64 v[130:131], 6, v[132:133]
	v_or_b32_e32 v64, v130, v146
	v_mov_b64_e32 v[132:133], s[52:53]
	s_movk_i32 s10, 0x1080
	v_mad_u64_u32 v[132:133], s[6:7], v64, s10, v[132:133]
	v_mad_i32_i24 v133, v131, s10, v133
	v_lshl_add_u64 v[130:131], v[132:133], 0, s[96:97]
	s_andn2_saveexec_b64 s[4:5], s[4:5]
	v_lshlrev_b64 v[130:131], 19, v[132:133]
	v_lshl_add_u64 v[130:131], v[148:149], 0, v[130:131]
	s_or_b64 exec, exec, s[4:5]
	v_lshl_add_u64 v[130:131], v[166:167], 1, v[130:131]
	s_mov_b64 s[4:5], 0
	s_waitcnt lgkmcnt(0)
	global_store_dwordx4 v[130:131], v[126:129], off
.LBB0_387:
	s_and_b64 vcc, exec, s[4:5]
	s_cbranch_vccz .LBB0_389
	v_add_u32_e32 v126, 0xfffffc80, v154
	v_cndmask_b32_e64 v129, v163, v165, s[0:1]
	v_cndmask_b32_e64 v128, v162, v164, s[0:1]
	v_lshl_add_u64 v[128:129], v[128:129], 2, s[28:29]
	v_ashrrev_i32_e32 v127, 31, v126
	v_lshl_add_u64 v[128:129], v[126:127], 2, v[128:129]
	global_store_dwordx4 v[128:129], v[118:121], off
	global_store_dwordx4 v[128:129], v[114:117], off offset:16
	s_nop 1
	v_lshl_add_u64 v[114:115], s[50:51], 0, v[158:159]
	v_lshl_add_u64 v[116:117], s[48:49], 0, v[160:161]
	v_cndmask_b32_e64 v115, v115, v117, s[0:1]
	v_cndmask_b32_e64 v114, v114, v116, s[0:1]
	v_lshl_add_u64 v[114:115], v[126:127], 1, v[114:115]
	global_store_dwordx4 v[114:115], v[122:125], off

; #define LAS __attribute__((address_space(3)))
;     DI void operator()(const f32x4 (&acc)[2][2][4][2], const Unit& u, int wr, int wc, int fr, int fq) const {
;     ...
;                 const int row = u.pm * 256 + ai * 128 + wr * 64 + m * 16 + fr;
;                 int s, b, t; rowinfo(row, s, b, t);
; #pragma unroll
;                 for (int bj = 0; bj < 2; ++bj) {
;                     const int col = u.pn * 256 + bj * 128 + wc * 32 + 8 * fq;
;                     u32x4 w; w.x = pk2(acc[ai][bj][m][0][0], acc[ai][bj][m][0][1]); w.y = pk2(acc[ai][bj][m][0][2], acc[ai][bj][m][0][3]); w.z = pk2(acc[ai][bj][m][1][0], acc[ai][bj][m][1][1]); w.w = pk2(acc[ai][bj][m][1][2], acc[ai][bj][m][1][3]);
;                     if (u.pn < 4) { *(u32x4*)(Q + (size_t)row * D + col) = w; }
;                     else if (u.pn < 8) {
;                         const int c = col - D;
;                         float* o = out + (s ? O_KS + (size_t)(row - MP) * D : O_KP + (size_t)row * D) + c; __builtin_nontemporal_store(acc[ai][bj][m][0], (f32x4*)o); __builtin_nontemporal_store(acc[ai][bj][m][1], (f32x4*)(o + 4));
;                         bf16_t* kb = s ? KS + ((size_t)b * LK + PAST + t) * D + c : KP + (size_t)row * D + c; *(u32x4*)kb = w;
;                     } else {
;                         const int c = col - 2 * D;
;                         float* o = out + (s ? O_VS + (size_t)(row - MP) * D : O_VP + (size_t)row * D) + c; __builtin_nontemporal_store(acc[ai][bj][m][0], (f32x4*)o); __builtin_nontemporal_store(acc[ai][bj][m][1], (f32x4*)(o + 4));
;                         LAS bf16_t* tp = (LAS bf16_t*)tw + (8 * fq) * 16 + fr;
;                         tp[0] = (bf16_t)(w.x & 0xffff); tp[16] = (bf16_t)(w.x >> 16); tp[32] = (bf16_t)(w.y & 0xffff); tp[48] = (bf16_t)(w.y >> 16);
;                         tp[64] = (bf16_t)(w.z & 0xffff); tp[80] = (bf16_t)(w.z >> 16); tp[96] = (bf16_t)(w.w & 0xffff); tp[112] = (bf16_t)(w.w >> 16);
;                         asm volatile("s_waitcnt lgkmcnt(0)" ::: "memory");
;                         const u32x4 tv = *(const LAS u32x4*)(tw + (lane >> 1) * 32 + (lane & 1) * 16);
;                         asm volatile("s_waitcnt lgkmcnt(0)" ::: "memory");
;                         const int cc = (col - 8 * fq) - 2 * D + (lane >> 1), h = cc >> 6, d = cc & 63, t0 = (t - fr) + (lane & 1) * 8;
.LBB0_392:
	v_or_b32_e32 v114, 16, v156
	s_movk_i32 s0, 0x7fff
	v_add_u32_e32 v116, 0xffff8010, v156
	v_cmp_lt_i32_e64 s[42:43], s0, v114
	v_lshrrev_b32_e32 v64, 6, v116
	v_cmp_gt_i32_e64 s[0:1], s81, v114
	v_mov_b32_e32 v117, s31
	s_and_b64 vcc, exec, s[40:41]
	v_cndmask_b32_e64 v115, 31, v235, s[0:1]
	v_cndmask_b32_e64 v120, v64, v117, s[0:1]
	v_ashrrev_i32_e32 v117, 31, v116
	v_bitop3_b32 v121, v115, v156, 16 bitop3:0xe0
	v_lshlrev_b64 v[116:117], 10, v[116:117]
	v_lshl_add_u64 v[130:131], v[116:117], 0, s[70:71]
	v_ashrrev_i32_e32 v115, 31, v114
	v_lshl_add_u64 v[126:127], v[116:117], 0, s[74:75]
	v_add_u32_e32 v116, 0x800, v121
	v_mov_b32_e32 v117, v65
	v_lshlrev_b64 v[118:119], 10, v[114:115]
	v_mad_i64_i32 v[116:117], s[4:5], v120, s22, v[116:117]
	v_lshl_add_u64 v[132:133], v[118:119], 0, s[72:73]
	v_add_u32_e32 v64, v121, v179
	v_lshlrev_b32_e32 v158, 4, v120
	v_lshl_add_u64 v[128:129], v[118:119], 0, s[76:77]
	v_lshlrev_b64 v[122:123], 11, v[116:117]
	v_lshlrev_b64 v[124:125], 11, v[114:115]
	v_cvt_pk_bf16_f32 v114, v110, v111
	v_cvt_pk_bf16_f32 v115, v112, v113
	v_cvt_pk_bf16_f32 v116, v106, v107
	v_cvt_pk_bf16_f32 v117, v108, v109
	s_mov_b64 s[4:5], -1
	s_cbranch_vccnz .LBB0_402
	s_and_b64 vcc, exec, s[38:39]
	s_cbranch_vccnz .LBB0_399
	v_cndmask_b32_e64 v119, v131, v133, s[0:1]
	v_cndmask_b32_e64 v118, v130, v132, s[0:1]
	v_lshl_add_u64 v[118:119], v[118:119], 2, s[28:29]
	v_mov_b32_e32 v155, v65
	v_lshl_add_u64 v[118:119], v[154:155], 2, v[118:119]
	v_add_co_u32_e32 v120, vcc, 0xffffe000, v118
	s_add_i32 s4, s26, 0xfffff800
	s_nop 0
	v_addc_co_u32_e32 v121, vcc, -1, v119, vcc
	v_add_co_u32_e32 v118, vcc, 0xffffe010, v118
	global_store_dwordx4 v[120:121], v[110:113], off
	s_nop 0
	v_addc_co_u32_e32 v119, vcc, -1, v119, vcc
	global_store_dwordx4 v[118:119], v[106:109], off
	ds_write_b16 v180, v114
	ds_write_b16_d16_hi v180, v114 offset:32
	ds_write_b16 v180, v115 offset:64
	ds_write_b16_d16_hi v180, v115 offset:96
	ds_write_b16 v180, v116 offset:128
	ds_write_b16_d16_hi v180, v116 offset:160
	ds_write_b16 v180, v117 offset:192
	ds_write_b16_d16_hi v180, v117 offset:224
	s_waitcnt lgkmcnt(0)
	v_add_u32_e32 v118, v181, v178
	ds_read_b128 v[118:121], v118
	s_waitcnt lgkmcnt(0)
	s_ashr_i32 s4, s4, 6
	v_add_u32_e32 v136, s4, v158
	v_ashrrev_i32_e32 v137, 31, v136
	s_and_saveexec_b64 s[4:5], s[42:43]
	s_xor_b64 s[4:5], exec, s[4:5]
	v_lshlrev_b64 v[134:135], 6, v[136:137]
	v_or_b32_e32 v134, v134, v146
	v_mov_b64_e32 v[136:137], s[52:53]
	s_movk_i32 s10, 0x1080
	v_mad_u64_u32 v[136:137], s[6:7], v134, s10, v[136:137]
	v_mad_i32_i24 v137, v135, s10, v137
	v_lshl_add_u64 v[134:135], v[136:137], 0, s[96:97]
	s_andn2_saveexec_b64 s[4:5], s[4:5]
	v_lshlrev_b64 v[134:135], 19, v[136:137]
	v_lshl_add_u64 v[134:135], v[148:149], 0, v[134:135]
	s_or_b64 exec, exec, s[4:5]
	v_lshl_add_u64 v[134:135], v[64:65], 1, v[134:135]
	s_mov_b64 s[4:5], 0
	s_waitcnt lgkmcnt(0)
	global_store_dwordx4 v[134:135], v[118:121], off
.LBB0_399:
	s_and_b64 vcc, exec, s[4:5]
	s_cbranch_vccz .LBB0_401
	v_add_u32_e32 v118, 0xfffffc00, v154
	v_cndmask_b32_e64 v121, v127, v129, s[0:1]
	v_cndmask_b32_e64 v120, v126, v128, s[0:1]
	v_lshl_add_u64 v[120:121], v[120:121], 2, s[28:29]
	v_ashrrev_i32_e32 v119, 31, v118
	v_lshl_add_u64 v[120:121], v[118:119], 2, v[120:121]
	global_store_dwordx4 v[120:121], v[110:113], off
	global_store_dwordx4 v[120:121], v[106:109], off offset:16
	s_nop 1
	v_lshl_add_u64 v[106:107], s[50:51], 0, v[122:123]
	v_lshl_add_u64 v[108:109], s[48:49], 0, v[124:125]
	v_cndmask_b32_e64 v107, v107, v109, s[0:1]
	v_cndmask_b32_e64 v106, v106, v108, s[0:1]
	v_lshl_add_u64 v[106:107], v[118:119], 1, v[106:107]
	global_store_dwordx4 v[106:107], v[114:117], off

; #define LAS __attribute__((address_space(3)))
;     DI void operator()(const f32x4 (&acc)[2][2][4][2], const Unit& u, int wr, int wc, int fr, int fq) const {
;     ...
;                 const int row = u.pm * 256 + ai * 128 + wr * 64 + m * 16 + fr;
;                 int s, b, t; rowinfo(row, s, b, t);
; #pragma unroll
;                 for (int bj = 0; bj < 2; ++bj) {
;                     const int col = u.pn * 256 + bj * 128 + wc * 32 + 8 * fq;
;                     u32x4 w; w.x = pk2(acc[ai][bj][m][0][0], acc[ai][bj][m][0][1]); w.y = pk2(acc[ai][bj][m][0][2], acc[ai][bj][m][0][3]); w.z = pk2(acc[ai][bj][m][1][0], acc[ai][bj][m][1][1]); w.w = pk2(acc[ai][bj][m][1][2], acc[ai][bj][m][1][3]);
;                     if (u.pn < 4) { *(u32x4*)(Q + (size_t)row * D + col) = w; }
;                     else if (u.pn < 8) {
;                         const int c = col - D;
;                         float* o = out + (s ? O_KS + (size_t)(row - MP) * D : O_KP + (size_t)row * D) + c; __builtin_nontemporal_store(acc[ai][bj][m][0], (f32x4*)o); __builtin_nontemporal_store(acc[ai][bj][m][1], (f32x4*)(o + 4));
;                         bf16_t* kb = s ? KS + ((size_t)b * LK + PAST + t) * D + c : KP + (size_t)row * D + c; *(u32x4*)kb = w;
;                     } else {
;                         const int c = col - 2 * D;
;                         float* o = out + (s ? O_VS + (size_t)(row - MP) * D : O_VP + (size_t)row * D) + c; __builtin_nontemporal_store(acc[ai][bj][m][0], (f32x4*)o); __builtin_nontemporal_store(acc[ai][bj][m][1], (f32x4*)(o + 4));
;                         LAS bf16_t* tp = (LAS bf16_t*)tw + (8 * fq) * 16 + fr;
;                         tp[0] = (bf16_t)(w.x & 0xffff); tp[16] = (bf16_t)(w.x >> 16); tp[32] = (bf16_t)(w.y & 0xffff); tp[48] = (bf16_t)(w.y >> 16);
;                         tp[64] = (bf16_t)(w.z & 0xffff); tp[80] = (bf16_t)(w.z >> 16); tp[96] = (bf16_t)(w.w & 0xffff); tp[112] = (bf16_t)(w.w >> 16);
;                         asm volatile("s_waitcnt lgkmcnt(0)" ::: "memory");
;                         const u32x4 tv = *(const LAS u32x4*)(tw + (lane >> 1) * 32 + (lane & 1) * 16);
;                         asm volatile("s_waitcnt lgkmcnt(0)" ::: "memory");
;                         const int cc = (col - 8 * fq) - 2 * D + (lane >> 1), h = cc >> 6, d = cc & 63, t0 = (t - fr) + (lane & 1) * 8;
.LBB0_404:
	v_cvt_pk_bf16_f32 v106, v102, v103
	v_cvt_pk_bf16_f32 v107, v104, v105
	v_cvt_pk_bf16_f32 v108, v98, v99
	v_cvt_pk_bf16_f32 v109, v100, v101
	s_and_b64 vcc, exec, s[40:41]
	s_mov_b64 s[4:5], -1
	s_cbranch_vccnz .LBB0_414
	s_and_b64 vcc, exec, s[38:39]
	s_cbranch_vccnz .LBB0_411
	v_cndmask_b32_e64 v111, v131, v133, s[0:1]
	v_cndmask_b32_e64 v110, v130, v132, s[0:1]
	v_lshl_add_u64 v[110:111], v[110:111], 2, s[28:29]
	v_mov_b32_e32 v155, v65
	v_lshl_add_u64 v[110:111], v[154:155], 2, v[110:111]
	v_add_co_u32_e32 v112, vcc, 0xffffe200, v110
	s_add_i32 s4, s26, 0xfffff880
	s_nop 0
	v_addc_co_u32_e32 v113, vcc, -1, v111, vcc
	v_add_co_u32_e32 v110, vcc, 0xffffe210, v110
	global_store_dwordx4 v[112:113], v[102:105], off
	s_nop 0
	v_addc_co_u32_e32 v111, vcc, -1, v111, vcc
	global_store_dwordx4 v[110:111], v[98:101], off
	ds_write_b16 v180, v106
	ds_write_b16_d16_hi v180, v106 offset:32
	ds_write_b16 v180, v107 offset:64
	ds_write_b16_d16_hi v180, v107 offset:96
	ds_write_b16 v180, v108 offset:128
	ds_write_b16_d16_hi v180, v108 offset:160
	ds_write_b16 v180, v109 offset:192
	ds_write_b16_d16_hi v180, v109 offset:224
	s_waitcnt lgkmcnt(0)
	v_add_u32_e32 v110, v181, v178
	ds_read_b128 v[110:113], v110
	s_waitcnt lgkmcnt(0)
	s_ashr_i32 s4, s4, 6
	v_add_u32_e32 v116, s4, v158
	v_ashrrev_i32_e32 v117, 31, v116
	s_and_saveexec_b64 s[4:5], s[42:43]
	s_xor_b64 s[4:5], exec, s[4:5]
	v_lshlrev_b64 v[114:115], 6, v[116:117]
	v_or_b32_e32 v114, v114, v146
	v_mov_b64_e32 v[116:117], s[52:53]
	s_movk_i32 s10, 0x1080
	v_mad_u64_u32 v[116:117], s[6:7], v114, s10, v[116:117]
	v_mad_i32_i24 v117, v115, s10, v117
	v_lshl_add_u64 v[114:115], v[116:117], 0, s[96:97]
	s_andn2_saveexec_b64 s[4:5], s[4:5]
	v_lshlrev_b64 v[114:115], 19, v[116:117]
	v_lshl_add_u64 v[114:115], v[148:149], 0, v[114:115]
	s_or_b64 exec, exec, s[4:5]
	v_lshl_add_u64 v[114:115], v[64:65], 1, v[114:115]
	s_mov_b64 s[4:5], 0
	s_waitcnt lgkmcnt(0)
	global_store_dwordx4 v[114:115], v[110:113], off
.LBB0_411:
	s_and_b64 vcc, exec, s[4:5]
	s_cbranch_vccz .LBB0_413
	v_add_u32_e32 v110, 0xfffffc80, v154
	v_cndmask_b32_e64 v113, v127, v129, s[0:1]
	v_cndmask_b32_e64 v112, v126, v128, s[0:1]
	v_lshl_add_u64 v[112:113], v[112:113], 2, s[28:29]
	v_ashrrev_i32_e32 v111, 31, v110
	v_lshl_add_u64 v[112:113], v[110:111], 2, v[112:113]
	global_store_dwordx4 v[112:113], v[102:105], off
	global_store_dwordx4 v[112:113], v[98:101], off offset:16
	s_nop 1
	v_lshl_add_u64 v[98:99], s[50:51], 0, v[122:123]
	v_lshl_add_u64 v[100:101], s[48:49], 0, v[124:125]
	v_cndmask_b32_e64 v99, v99, v101, s[0:1]
	v_cndmask_b32_e64 v98, v98, v100, s[0:1]
	v_lshl_add_u64 v[98:99], v[110:111], 1, v[98:99]
	global_store_dwordx4 v[98:99], v[106:109], off

; #define LAS __attribute__((address_space(3)))
;     DI void operator()(const f32x4 (&acc)[2][2][4][2], const Unit& u, int wr, int wc, int fr, int fq) const {
;     ...
;                 const int row = u.pm * 256 + ai * 128 + wr * 64 + m * 16 + fr;
;                 int s, b, t; rowinfo(row, s, b, t);
; #pragma unroll
;                 for (int bj = 0; bj < 2; ++bj) {
;                     const int col = u.pn * 256 + bj * 128 + wc * 32 + 8 * fq;
;                     u32x4 w; w.x = pk2(acc[ai][bj][m][0][0], acc[ai][bj][m][0][1]); w.y = pk2(acc[ai][bj][m][0][2], acc[ai][bj][m][0][3]); w.z = pk2(acc[ai][bj][m][1][0], acc[ai][bj][m][1][1]); w.w = pk2(acc[ai][bj][m][1][2], acc[ai][bj][m][1][3]);
;                     if (u.pn < 4) { *(u32x4*)(Q + (size_t)row * D + col) = w; }
;                     else if (u.pn < 8) {
;                         const int c = col - D;
;                         float* o = out + (s ? O_KS + (size_t)(row - MP) * D : O_KP + (size_t)row * D) + c; __builtin_nontemporal_store(acc[ai][bj][m][0], (f32x4*)o); __builtin_nontemporal_store(acc[ai][bj][m][1], (f32x4*)(o + 4));
;                         bf16_t* kb = s ? KS + ((size_t)b * LK + PAST + t) * D + c : KP + (size_t)row * D + c; *(u32x4*)kb = w;
;                     } else {
;                         const int c = col - 2 * D;
;                         float* o = out + (s ? O_VS + (size_t)(row - MP) * D : O_VP + (size_t)row * D) + c; __builtin_nontemporal_store(acc[ai][bj][m][0], (f32x4*)o); __builtin_nontemporal_store(acc[ai][bj][m][1], (f32x4*)(o + 4));
;                         LAS bf16_t* tp = (LAS bf16_t*)tw + (8 * fq) * 16 + fr;
;                         tp[0] = (bf16_t)(w.x & 0xffff); tp[16] = (bf16_t)(w.x >> 16); tp[32] = (bf16_t)(w.y & 0xffff); tp[48] = (bf16_t)(w.y >> 16);
;                         tp[64] = (bf16_t)(w.z & 0xffff); tp[80] = (bf16_t)(w.z >> 16); tp[96] = (bf16_t)(w.w & 0xffff); tp[112] = (bf16_t)(w.w >> 16);
;                         asm volatile("s_waitcnt lgkmcnt(0)" ::: "memory");
;                         const u32x4 tv = *(const LAS u32x4*)(tw + (lane >> 1) * 32 + (lane & 1) * 16);
;                         asm volatile("s_waitcnt lgkmcnt(0)" ::: "memory");
;                         const int cc = (col - 8 * fq) - 2 * D + (lane >> 1), h = cc >> 6, d = cc & 63, t0 = (t - fr) + (lane & 1) * 8;
.LBB0_416:
	v_or_b32_e32 v98, 32, v156
	s_movk_i32 s0, 0x7fff
	v_add_u32_e32 v100, 0xffff8020, v156
	v_cmp_lt_i32_e64 s[42:43], s0, v98
	v_lshrrev_b32_e32 v64, 6, v100
	v_cmp_gt_i32_e64 s[0:1], s81, v98
	v_mov_b32_e32 v101, s31
	s_and_b64 vcc, exec, s[40:41]
	v_cndmask_b32_e64 v99, 47, v236, s[0:1]
	v_cndmask_b32_e64 v104, v64, v101, s[0:1]
	v_ashrrev_i32_e32 v101, 31, v100
	v_bitop3_b32 v105, v99, v156, 32 bitop3:0xe0
	v_lshlrev_b64 v[100:101], 10, v[100:101]
	v_lshl_add_u64 v[114:115], v[100:101], 0, s[70:71]
	v_ashrrev_i32_e32 v99, 31, v98
	v_lshl_add_u64 v[110:111], v[100:101], 0, s[74:75]
	v_add_u32_e32 v100, 0x800, v105
	v_mov_b32_e32 v101, v65
	v_lshlrev_b64 v[102:103], 10, v[98:99]
	v_mad_i64_i32 v[100:101], s[4:5], v104, s22, v[100:101]
	v_lshl_add_u64 v[116:117], v[102:103], 0, s[72:73]
	v_add_u32_e32 v64, v105, v179
	v_lshlrev_b32_e32 v122, 4, v104
	v_lshl_add_u64 v[112:113], v[102:103], 0, s[76:77]
	v_lshlrev_b64 v[106:107], 11, v[100:101]
	v_lshlrev_b64 v[108:109], 11, v[98:99]
	v_cvt_pk_bf16_f32 v98, v94, v95
	v_cvt_pk_bf16_f32 v99, v96, v97
	v_cvt_pk_bf16_f32 v100, v90, v91
	v_cvt_pk_bf16_f32 v101, v92, v93
	s_mov_b64 s[4:5], -1
	s_cbranch_vccnz .LBB0_426
	s_and_b64 vcc, exec, s[38:39]
	s_cbranch_vccnz .LBB0_423
	v_cndmask_b32_e64 v103, v115, v117, s[0:1]
	v_cndmask_b32_e64 v102, v114, v116, s[0:1]
	v_lshl_add_u64 v[102:103], v[102:103], 2, s[28:29]
	v_mov_b32_e32 v155, v65
	v_lshl_add_u64 v[102:103], v[154:155], 2, v[102:103]
	v_add_co_u32_e32 v104, vcc, 0xffffe000, v102
	s_add_i32 s4, s26, 0xfffff800
	s_nop 0
	v_addc_co_u32_e32 v105, vcc, -1, v103, vcc
	v_add_co_u32_e32 v102, vcc, 0xffffe010, v102
	global_store_dwordx4 v[104:105], v[94:97], off
	s_nop 0
	v_addc_co_u32_e32 v103, vcc, -1, v103, vcc
	global_store_dwordx4 v[102:103], v[90:93], off
	ds_write_b16 v180, v98
	ds_write_b16_d16_hi v180, v98 offset:32
	ds_write_b16 v180, v99 offset:64
	ds_write_b16_d16_hi v180, v99 offset:96
	ds_write_b16 v180, v100 offset:128
	ds_write_b16_d16_hi v180, v100 offset:160
	ds_write_b16 v180, v101 offset:192
	ds_write_b16_d16_hi v180, v101 offset:224
	s_waitcnt lgkmcnt(0)
	v_add_u32_e32 v102, v181, v178
	ds_read_b128 v[102:105], v102
	s_waitcnt lgkmcnt(0)
	s_ashr_i32 s4, s4, 6
	v_add_u32_e32 v120, s4, v122
	v_ashrrev_i32_e32 v121, 31, v120
	s_and_saveexec_b64 s[4:5], s[42:43]
	s_xor_b64 s[4:5], exec, s[4:5]
	v_lshlrev_b64 v[118:119], 6, v[120:121]
	v_or_b32_e32 v118, v118, v146
	v_mov_b64_e32 v[120:121], s[52:53]
	s_movk_i32 s10, 0x1080
	v_mad_u64_u32 v[120:121], s[6:7], v118, s10, v[120:121]
	v_mad_i32_i24 v121, v119, s10, v121
	v_lshl_add_u64 v[118:119], v[120:121], 0, s[96:97]
	s_andn2_saveexec_b64 s[4:5], s[4:5]
	v_lshlrev_b64 v[118:119], 19, v[120:121]
	v_lshl_add_u64 v[118:119], v[148:149], 0, v[118:119]
	s_or_b64 exec, exec, s[4:5]
	v_lshl_add_u64 v[118:119], v[64:65], 1, v[118:119]
	s_mov_b64 s[4:5], 0
	s_waitcnt lgkmcnt(0)
	global_store_dwordx4 v[118:119], v[102:105], off
.LBB0_423:
	s_and_b64 vcc, exec, s[4:5]
	s_cbranch_vccz .LBB0_425
	v_add_u32_e32 v102, 0xfffffc00, v154
	v_cndmask_b32_e64 v105, v111, v113, s[0:1]
	v_cndmask_b32_e64 v104, v110, v112, s[0:1]
	v_lshl_add_u64 v[104:105], v[104:105], 2, s[28:29]
	v_ashrrev_i32_e32 v103, 31, v102
	v_lshl_add_u64 v[104:105], v[102:103], 2, v[104:105]
	global_store_dwordx4 v[104:105], v[94:97], off
	global_store_dwordx4 v[104:105], v[90:93], off offset:16
	s_nop 1
	v_lshl_add_u64 v[90:91], s[50:51], 0, v[106:107]
	v_lshl_add_u64 v[92:93], s[48:49], 0, v[108:109]
	v_cndmask_b32_e64 v91, v91, v93, s[0:1]
	v_cndmask_b32_e64 v90, v90, v92, s[0:1]
	v_lshl_add_u64 v[90:91], v[102:103], 1, v[90:91]
	global_store_dwordx4 v[90:91], v[98:101], off

; #define LAS __attribute__((address_space(3)))
;     DI void operator()(const f32x4 (&acc)[2][2][4][2], const Unit& u, int wr, int wc, int fr, int fq) const {
;     ...
;                 const int row = u.pm * 256 + ai * 128 + wr * 64 + m * 16 + fr;
;                 int s, b, t; rowinfo(row, s, b, t);
; #pragma unroll
;                 for (int bj = 0; bj < 2; ++bj) {
;                     const int col = u.pn * 256 + bj * 128 + wc * 32 + 8 * fq;
;                     u32x4 w; w.x = pk2(acc[ai][bj][m][0][0], acc[ai][bj][m][0][1]); w.y = pk2(acc[ai][bj][m][0][2], acc[ai][bj][m][0][3]); w.z = pk2(acc[ai][bj][m][1][0], acc[ai][bj][m][1][1]); w.w = pk2(acc[ai][bj][m][1][2], acc[ai][bj][m][1][3]);
;                     if (u.pn < 4) { *(u32x4*)(Q + (size_t)row * D + col) = w; }
;                     else if (u.pn < 8) {
;                         const int c = col - D;
;                         float* o = out + (s ? O_KS + (size_t)(row - MP) * D : O_KP + (size_t)row * D) + c; __builtin_nontemporal_store(acc[ai][bj][m][0], (f32x4*)o); __builtin_nontemporal_store(acc[ai][bj][m][1], (f32x4*)(o + 4));
;                         bf16_t* kb = s ? KS + ((size_t)b * LK + PAST + t) * D + c : KP + (size_t)row * D + c; *(u32x4*)kb = w;
;                     } else {
;                         const int c = col - 2 * D;
;                         float* o = out + (s ? O_VS + (size_t)(row - MP) * D : O_VP + (size_t)row * D) + c; __builtin_nontemporal_store(acc[ai][bj][m][0], (f32x4*)o); __builtin_nontemporal_store(acc[ai][bj][m][1], (f32x4*)(o + 4));
;                         LAS bf16_t* tp = (LAS bf16_t*)tw + (8 * fq) * 16 + fr;
;                         tp[0] = (bf16_t)(w.x & 0xffff); tp[16] = (bf16_t)(w.x >> 16); tp[32] = (bf16_t)(w.y & 0xffff); tp[48] = (bf16_t)(w.y >> 16);
;                         tp[64] = (bf16_t)(w.z & 0xffff); tp[80] = (bf16_t)(w.z >> 16); tp[96] = (bf16_t)(w.w & 0xffff); tp[112] = (bf16_t)(w.w >> 16);
;                         asm volatile("s_waitcnt lgkmcnt(0)" ::: "memory");
;                         const u32x4 tv = *(const LAS u32x4*)(tw + (lane >> 1) * 32 + (lane & 1) * 16);
;                         asm volatile("s_waitcnt lgkmcnt(0)" ::: "memory");
;                         const int cc = (col - 8 * fq) - 2 * D + (lane >> 1), h = cc >> 6, d = cc & 63, t0 = (t - fr) + (lane & 1) * 8;
.LBB0_428:
	v_cvt_pk_bf16_f32 v90, v86, v87
	v_cvt_pk_bf16_f32 v91, v88, v89
	v_cvt_pk_bf16_f32 v92, v82, v83
	v_cvt_pk_bf16_f32 v93, v84, v85
	s_and_b64 vcc, exec, s[40:41]
	s_mov_b64 s[4:5], -1
	s_cbranch_vccnz .LBB0_438
	s_and_b64 vcc, exec, s[38:39]
	s_cbranch_vccnz .LBB0_435
	v_cndmask_b32_e64 v95, v115, v117, s[0:1]
	v_cndmask_b32_e64 v94, v114, v116, s[0:1]
	v_lshl_add_u64 v[94:95], v[94:95], 2, s[28:29]
	v_mov_b32_e32 v155, v65
	v_lshl_add_u64 v[94:95], v[154:155], 2, v[94:95]
	v_add_co_u32_e32 v96, vcc, 0xffffe200, v94
	s_add_i32 s4, s26, 0xfffff880
	s_nop 0
	v_addc_co_u32_e32 v97, vcc, -1, v95, vcc
	v_add_co_u32_e32 v94, vcc, 0xffffe210, v94
	global_store_dwordx4 v[96:97], v[86:89], off
	s_nop 0
	v_addc_co_u32_e32 v95, vcc, -1, v95, vcc
	global_store_dwordx4 v[94:95], v[82:85], off
	ds_write_b16 v180, v90
	ds_write_b16_d16_hi v180, v90 offset:32
	ds_write_b16 v180, v91 offset:64
	ds_write_b16_d16_hi v180, v91 offset:96
	ds_write_b16 v180, v92 offset:128
	ds_write_b16_d16_hi v180, v92 offset:160
	ds_write_b16 v180, v93 offset:192
	ds_write_b16_d16_hi v180, v93 offset:224
	s_waitcnt lgkmcnt(0)
	v_add_u32_e32 v94, v181, v178
	ds_read_b128 v[94:97], v94
	s_waitcnt lgkmcnt(0)
	s_ashr_i32 s4, s4, 6
	v_add_u32_e32 v100, s4, v122
	v_ashrrev_i32_e32 v101, 31, v100
	s_and_saveexec_b64 s[4:5], s[42:43]
	s_xor_b64 s[4:5], exec, s[4:5]
	v_lshlrev_b64 v[98:99], 6, v[100:101]
	v_or_b32_e32 v98, v98, v146
	v_mov_b64_e32 v[100:101], s[52:53]
	s_movk_i32 s10, 0x1080
	v_mad_u64_u32 v[100:101], s[6:7], v98, s10, v[100:101]
	v_mad_i32_i24 v101, v99, s10, v101
	v_lshl_add_u64 v[98:99], v[100:101], 0, s[96:97]
	s_andn2_saveexec_b64 s[4:5], s[4:5]
	v_lshlrev_b64 v[98:99], 19, v[100:101]
	v_lshl_add_u64 v[98:99], v[148:149], 0, v[98:99]
	s_or_b64 exec, exec, s[4:5]
	v_lshl_add_u64 v[98:99], v[64:65], 1, v[98:99]
	s_mov_b64 s[4:5], 0
	s_waitcnt lgkmcnt(0)
	global_store_dwordx4 v[98:99], v[94:97], off
.LBB0_435:
	s_and_b64 vcc, exec, s[4:5]
	s_cbranch_vccz .LBB0_437
	v_add_u32_e32 v94, 0xfffffc80, v154
	v_cndmask_b32_e64 v97, v111, v113, s[0:1]
	v_cndmask_b32_e64 v96, v110, v112, s[0:1]
	v_lshl_add_u64 v[96:97], v[96:97], 2, s[28:29]
	v_ashrrev_i32_e32 v95, 31, v94
	v_lshl_add_u64 v[96:97], v[94:95], 2, v[96:97]
	global_store_dwordx4 v[96:97], v[86:89], off
	global_store_dwordx4 v[96:97], v[82:85], off offset:16
	s_nop 1
	v_lshl_add_u64 v[82:83], s[50:51], 0, v[106:107]
	v_lshl_add_u64 v[84:85], s[48:49], 0, v[108:109]
	v_cndmask_b32_e64 v83, v83, v85, s[0:1]
	v_cndmask_b32_e64 v82, v82, v84, s[0:1]
	v_lshl_add_u64 v[82:83], v[94:95], 1, v[82:83]
	global_store_dwordx4 v[82:83], v[90:93], off

; #define LAS __attribute__((address_space(3)))
;     DI void operator()(const f32x4 (&acc)[2][2][4][2], const Unit& u, int wr, int wc, int fr, int fq) const {
;     ...
;                 const int row = u.pm * 256 + ai * 128 + wr * 64 + m * 16 + fr;
;                 int s, b, t; rowinfo(row, s, b, t);
; #pragma unroll
;                 for (int bj = 0; bj < 2; ++bj) {
;                     const int col = u.pn * 256 + bj * 128 + wc * 32 + 8 * fq;
;                     u32x4 w; w.x = pk2(acc[ai][bj][m][0][0], acc[ai][bj][m][0][1]); w.y = pk2(acc[ai][bj][m][0][2], acc[ai][bj][m][0][3]); w.z = pk2(acc[ai][bj][m][1][0], acc[ai][bj][m][1][1]); w.w = pk2(acc[ai][bj][m][1][2], acc[ai][bj][m][1][3]);
;                     if (u.pn < 4) { *(u32x4*)(Q + (size_t)row * D + col) = w; }
;                     else if (u.pn < 8) {
;                         const int c = col - D;
;                         float* o = out + (s ? O_KS + (size_t)(row - MP) * D : O_KP + (size_t)row * D) + c; __builtin_nontemporal_store(acc[ai][bj][m][0], (f32x4*)o); __builtin_nontemporal_store(acc[ai][bj][m][1], (f32x4*)(o + 4));
;                         bf16_t* kb = s ? KS + ((size_t)b * LK + PAST + t) * D + c : KP + (size_t)row * D + c; *(u32x4*)kb = w;
;                     } else {
;                         const int c = col - 2 * D;
;                         float* o = out + (s ? O_VS + (size_t)(row - MP) * D : O_VP + (size_t)row * D) + c; __builtin_nontemporal_store(acc[ai][bj][m][0], (f32x4*)o); __builtin_nontemporal_store(acc[ai][bj][m][1], (f32x4*)(o + 4));
;                         LAS bf16_t* tp = (LAS bf16_t*)tw + (8 * fq) * 16 + fr;
;                         tp[0] = (bf16_t)(w.x & 0xffff); tp[16] = (bf16_t)(w.x >> 16); tp[32] = (bf16_t)(w.y & 0xffff); tp[48] = (bf16_t)(w.y >> 16);
;                         tp[64] = (bf16_t)(w.z & 0xffff); tp[80] = (bf16_t)(w.z >> 16); tp[96] = (bf16_t)(w.w & 0xffff); tp[112] = (bf16_t)(w.w >> 16);
;                         asm volatile("s_waitcnt lgkmcnt(0)" ::: "memory");
;                         const u32x4 tv = *(const LAS u32x4*)(tw + (lane >> 1) * 32 + (lane & 1) * 16);
;                         asm volatile("s_waitcnt lgkmcnt(0)" ::: "memory");
;                         const int cc = (col - 8 * fq) - 2 * D + (lane >> 1), h = cc >> 6, d = cc & 63, t0 = (t - fr) + (lane & 1) * 8;
.LBB0_440:
	v_or_b32_e32 v82, 48, v156
	s_movk_i32 s0, 0x7fff
	v_add_u32_e32 v84, 0xffff8030, v156
	v_cmp_lt_i32_e64 s[42:43], s0, v82
	v_lshrrev_b32_e32 v64, 6, v84
	v_cmp_gt_i32_e64 s[0:1], s81, v82
	v_mov_b32_e32 v85, s31
	s_and_b64 vcc, exec, s[40:41]
	v_cndmask_b32_e64 v83, 63, v229, s[0:1]
	v_cndmask_b32_e64 v88, v64, v85, s[0:1]
	v_ashrrev_i32_e32 v85, 31, v84
	v_bitop3_b32 v89, v83, v156, 48 bitop3:0xe0
	v_lshlrev_b64 v[84:85], 10, v[84:85]
	v_lshl_add_u64 v[98:99], v[84:85], 0, s[70:71]
	v_ashrrev_i32_e32 v83, 31, v82
	v_lshl_add_u64 v[94:95], v[84:85], 0, s[74:75]
	v_add_u32_e32 v84, 0x800, v89
	v_mov_b32_e32 v85, v65
	v_lshlrev_b64 v[86:87], 10, v[82:83]
	v_mad_i64_i32 v[84:85], s[4:5], v88, s22, v[84:85]
	v_lshl_add_u64 v[100:101], v[86:87], 0, s[72:73]
	v_add_u32_e32 v64, v89, v179
	v_lshlrev_b32_e32 v106, 4, v88
	v_lshl_add_u64 v[96:97], v[86:87], 0, s[76:77]
	v_lshlrev_b64 v[90:91], 11, v[84:85]
	v_lshlrev_b64 v[92:93], 11, v[82:83]
	v_cvt_pk_bf16_f32 v82, v78, v79
	v_cvt_pk_bf16_f32 v83, v80, v81
	v_cvt_pk_bf16_f32 v84, v74, v75
	v_cvt_pk_bf16_f32 v85, v76, v77
	s_mov_b64 s[4:5], -1
	s_cbranch_vccnz .LBB0_450
	s_and_b64 vcc, exec, s[38:39]
	s_cbranch_vccnz .LBB0_447
	v_cndmask_b32_e64 v87, v99, v101, s[0:1]
	v_cndmask_b32_e64 v86, v98, v100, s[0:1]
	v_lshl_add_u64 v[86:87], v[86:87], 2, s[28:29]
	v_mov_b32_e32 v155, v65
	v_lshl_add_u64 v[86:87], v[154:155], 2, v[86:87]
	v_add_co_u32_e32 v88, vcc, 0xffffe000, v86
	s_add_i32 s4, s26, 0xfffff800
	s_nop 0
	v_addc_co_u32_e32 v89, vcc, -1, v87, vcc
	v_add_co_u32_e32 v86, vcc, 0xffffe010, v86
	global_store_dwordx4 v[88:89], v[78:81], off
	s_nop 0
	v_addc_co_u32_e32 v87, vcc, -1, v87, vcc
	global_store_dwordx4 v[86:87], v[74:77], off
	ds_write_b16 v180, v82
	ds_write_b16_d16_hi v180, v82 offset:32
	ds_write_b16 v180, v83 offset:64
	ds_write_b16_d16_hi v180, v83 offset:96
	ds_write_b16 v180, v84 offset:128
	ds_write_b16_d16_hi v180, v84 offset:160
	ds_write_b16 v180, v85 offset:192
	ds_write_b16_d16_hi v180, v85 offset:224
	s_waitcnt lgkmcnt(0)
	v_add_u32_e32 v86, v181, v178
	ds_read_b128 v[86:89], v86
	s_waitcnt lgkmcnt(0)
	s_ashr_i32 s4, s4, 6
	v_add_u32_e32 v104, s4, v106
	v_ashrrev_i32_e32 v105, 31, v104
	s_and_saveexec_b64 s[4:5], s[42:43]
	s_xor_b64 s[4:5], exec, s[4:5]
	v_lshlrev_b64 v[102:103], 6, v[104:105]
	v_or_b32_e32 v102, v102, v146
	v_mov_b64_e32 v[104:105], s[52:53]
	s_movk_i32 s10, 0x1080
	v_mad_u64_u32 v[104:105], s[6:7], v102, s10, v[104:105]
	v_mad_i32_i24 v105, v103, s10, v105
	v_lshl_add_u64 v[102:103], v[104:105], 0, s[96:97]
	s_andn2_saveexec_b64 s[4:5], s[4:5]
	v_lshlrev_b64 v[102:103], 19, v[104:105]
	v_lshl_add_u64 v[102:103], v[148:149], 0, v[102:103]
	s_or_b64 exec, exec, s[4:5]
	v_lshl_add_u64 v[102:103], v[64:65], 1, v[102:103]
	s_mov_b64 s[4:5], 0
	s_waitcnt lgkmcnt(0)
	global_store_dwordx4 v[102:103], v[86:89], off
.LBB0_447:
	s_and_b64 vcc, exec, s[4:5]
	s_cbranch_vccz .LBB0_449
	v_add_u32_e32 v86, 0xfffffc00, v154
	v_cndmask_b32_e64 v89, v95, v97, s[0:1]
	v_cndmask_b32_e64 v88, v94, v96, s[0:1]
	v_lshl_add_u64 v[88:89], v[88:89], 2, s[28:29]
	v_ashrrev_i32_e32 v87, 31, v86
	v_lshl_add_u64 v[88:89], v[86:87], 2, v[88:89]
	global_store_dwordx4 v[88:89], v[78:81], off
	global_store_dwordx4 v[88:89], v[74:77], off offset:16
	s_nop 1
	v_lshl_add_u64 v[74:75], s[50:51], 0, v[90:91]
	v_lshl_add_u64 v[76:77], s[48:49], 0, v[92:93]
	v_cndmask_b32_e64 v75, v75, v77, s[0:1]
	v_cndmask_b32_e64 v74, v74, v76, s[0:1]
	v_lshl_add_u64 v[74:75], v[86:87], 1, v[74:75]
	global_store_dwordx4 v[74:75], v[82:85], off

; #define LAS __attribute__((address_space(3)))
;     DI void operator()(const f32x4 (&acc)[2][2][4][2], const Unit& u, int wr, int wc, int fr, int fq) const {
;     ...
;                 const int row = u.pm * 256 + ai * 128 + wr * 64 + m * 16 + fr;
;                 int s, b, t; rowinfo(row, s, b, t);
; #pragma unroll
;                 for (int bj = 0; bj < 2; ++bj) {
;                     const int col = u.pn * 256 + bj * 128 + wc * 32 + 8 * fq;
;                     u32x4 w; w.x = pk2(acc[ai][bj][m][0][0], acc[ai][bj][m][0][1]); w.y = pk2(acc[ai][bj][m][0][2], acc[ai][bj][m][0][3]); w.z = pk2(acc[ai][bj][m][1][0], acc[ai][bj][m][1][1]); w.w = pk2(acc[ai][bj][m][1][2], acc[ai][bj][m][1][3]);
;                     if (u.pn < 4) { *(u32x4*)(Q + (size_t)row * D + col) = w; }
;                     else if (u.pn < 8) {
;                         const int c = col - D;
;                         float* o = out + (s ? O_KS + (size_t)(row - MP) * D : O_KP + (size_t)row * D) + c; __builtin_nontemporal_store(acc[ai][bj][m][0], (f32x4*)o); __builtin_nontemporal_store(acc[ai][bj][m][1], (f32x4*)(o + 4));
;                         bf16_t* kb = s ? KS + ((size_t)b * LK + PAST + t) * D + c : KP + (size_t)row * D + c; *(u32x4*)kb = w;
;                     } else {
;                         const int c = col - 2 * D;
;                         float* o = out + (s ? O_VS + (size_t)(row - MP) * D : O_VP + (size_t)row * D) + c; __builtin_nontemporal_store(acc[ai][bj][m][0], (f32x4*)o); __builtin_nontemporal_store(acc[ai][bj][m][1], (f32x4*)(o + 4));
;                         LAS bf16_t* tp = (LAS bf16_t*)tw + (8 * fq) * 16 + fr;
;                         tp[0] = (bf16_t)(w.x & 0xffff); tp[16] = (bf16_t)(w.x >> 16); tp[32] = (bf16_t)(w.y & 0xffff); tp[48] = (bf16_t)(w.y >> 16);
;                         tp[64] = (bf16_t)(w.z & 0xffff); tp[80] = (bf16_t)(w.z >> 16); tp[96] = (bf16_t)(w.w & 0xffff); tp[112] = (bf16_t)(w.w >> 16);
;                         asm volatile("s_waitcnt lgkmcnt(0)" ::: "memory");
;                         const u32x4 tv = *(const LAS u32x4*)(tw + (lane >> 1) * 32 + (lane & 1) * 16);
;                         asm volatile("s_waitcnt lgkmcnt(0)" ::: "memory");
;                         const int cc = (col - 8 * fq) - 2 * D + (lane >> 1), h = cc >> 6, d = cc & 63, t0 = (t - fr) + (lane & 1) * 8;
.LBB0_452:
	v_cvt_pk_bf16_f32 v74, v70, v71
	v_cvt_pk_bf16_f32 v75, v72, v73
	v_cvt_pk_bf16_f32 v76, v66, v67
	v_cvt_pk_bf16_f32 v77, v68, v69
	s_and_b64 vcc, exec, s[40:41]
	s_mov_b64 s[4:5], -1
	s_cbranch_vccnz .LBB0_462
	s_and_b64 vcc, exec, s[38:39]
	s_cbranch_vccnz .LBB0_459
	v_cndmask_b32_e64 v79, v99, v101, s[0:1]
	v_cndmask_b32_e64 v78, v98, v100, s[0:1]
	v_lshl_add_u64 v[78:79], v[78:79], 2, s[28:29]
	v_mov_b32_e32 v155, v65
	v_lshl_add_u64 v[78:79], v[154:155], 2, v[78:79]
	v_add_co_u32_e32 v80, vcc, 0xffffe200, v78
	s_add_i32 s4, s26, 0xfffff880
	s_nop 0
	v_addc_co_u32_e32 v81, vcc, -1, v79, vcc
	v_add_co_u32_e32 v78, vcc, 0xffffe210, v78
	global_store_dwordx4 v[80:81], v[70:73], off
	s_nop 0
	v_addc_co_u32_e32 v79, vcc, -1, v79, vcc
	global_store_dwordx4 v[78:79], v[66:69], off
	ds_write_b16 v180, v74
	ds_write_b16_d16_hi v180, v74 offset:32
	ds_write_b16 v180, v75 offset:64
	ds_write_b16_d16_hi v180, v75 offset:96
	ds_write_b16 v180, v76 offset:128
	ds_write_b16_d16_hi v180, v76 offset:160
	ds_write_b16 v180, v77 offset:192
	ds_write_b16_d16_hi v180, v77 offset:224
	s_waitcnt lgkmcnt(0)
	v_add_u32_e32 v78, v181, v178
	ds_read_b128 v[78:81], v78
	s_waitcnt lgkmcnt(0)
	s_ashr_i32 s4, s4, 6
	v_add_u32_e32 v84, s4, v106
	v_ashrrev_i32_e32 v85, 31, v84
	s_and_saveexec_b64 s[4:5], s[42:43]
	s_xor_b64 s[4:5], exec, s[4:5]
	v_lshlrev_b64 v[82:83], 6, v[84:85]
	v_or_b32_e32 v82, v82, v146
	v_mov_b64_e32 v[84:85], s[52:53]
	s_movk_i32 s10, 0x1080
	v_mad_u64_u32 v[84:85], s[6:7], v82, s10, v[84:85]
	v_mad_i32_i24 v85, v83, s10, v85
	v_lshl_add_u64 v[82:83], v[84:85], 0, s[96:97]
	s_andn2_saveexec_b64 s[4:5], s[4:5]
	v_lshlrev_b64 v[82:83], 19, v[84:85]
	v_lshl_add_u64 v[82:83], v[148:149], 0, v[82:83]
	s_or_b64 exec, exec, s[4:5]
	v_lshl_add_u64 v[82:83], v[64:65], 1, v[82:83]
	s_mov_b64 s[4:5], 0
	s_waitcnt lgkmcnt(0)
	global_store_dwordx4 v[82:83], v[78:81], off
.LBB0_459:
	s_and_b64 vcc, exec, s[4:5]
	s_cbranch_vccz .LBB0_461
	v_add_u32_e32 v78, 0xfffffc80, v154
	v_cndmask_b32_e64 v81, v95, v97, s[0:1]
	v_cndmask_b32_e64 v80, v94, v96, s[0:1]
	v_lshl_add_u64 v[80:81], v[80:81], 2, s[28:29]
	v_ashrrev_i32_e32 v79, 31, v78
	v_lshl_add_u64 v[80:81], v[78:79], 2, v[80:81]
	global_store_dwordx4 v[80:81], v[70:73], off
	global_store_dwordx4 v[80:81], v[66:69], off offset:16
	s_nop 1
	v_lshl_add_u64 v[66:67], s[50:51], 0, v[90:91]
	v_lshl_add_u64 v[68:69], s[48:49], 0, v[92:93]
	v_cndmask_b32_e64 v67, v67, v69, s[0:1]
	v_cndmask_b32_e64 v66, v66, v68, s[0:1]
	v_lshl_add_u64 v[66:67], v[78:79], 1, v[66:67]
	global_store_dwordx4 v[66:67], v[74:77], off

; #define LAS __attribute__((address_space(3)))
;     DI void operator()(const f32x4 (&acc)[2][2][4][2], const Unit& u, int wr, int wc, int fr, int fq) const {
;     ...
;                 const int row = u.pm * 256 + ai * 128 + wr * 64 + m * 16 + fr;
;                 int s, b, t; rowinfo(row, s, b, t);
; #pragma unroll
;                 for (int bj = 0; bj < 2; ++bj) {
;                     const int col = u.pn * 256 + bj * 128 + wc * 32 + 8 * fq;
;                     u32x4 w; w.x = pk2(acc[ai][bj][m][0][0], acc[ai][bj][m][0][1]); w.y = pk2(acc[ai][bj][m][0][2], acc[ai][bj][m][0][3]); w.z = pk2(acc[ai][bj][m][1][0], acc[ai][bj][m][1][1]); w.w = pk2(acc[ai][bj][m][1][2], acc[ai][bj][m][1][3]);
;                     if (u.pn < 4) { *(u32x4*)(Q + (size_t)row * D + col) = w; }
;                     else if (u.pn < 8) {
;                         const int c = col - D;
;                         float* o = out + (s ? O_KS + (size_t)(row - MP) * D : O_KP + (size_t)row * D) + c; __builtin_nontemporal_store(acc[ai][bj][m][0], (f32x4*)o); __builtin_nontemporal_store(acc[ai][bj][m][1], (f32x4*)(o + 4));
;                         bf16_t* kb = s ? KS + ((size_t)b * LK + PAST + t) * D + c : KP + (size_t)row * D + c; *(u32x4*)kb = w;
;                     } else {
;                         const int c = col - 2 * D;
;                         float* o = out + (s ? O_VS + (size_t)(row - MP) * D : O_VP + (size_t)row * D) + c; __builtin_nontemporal_store(acc[ai][bj][m][0], (f32x4*)o); __builtin_nontemporal_store(acc[ai][bj][m][1], (f32x4*)(o + 4));
;                         LAS bf16_t* tp = (LAS bf16_t*)tw + (8 * fq) * 16 + fr;
;                         tp[0] = (bf16_t)(w.x & 0xffff); tp[16] = (bf16_t)(w.x >> 16); tp[32] = (bf16_t)(w.y & 0xffff); tp[48] = (bf16_t)(w.y >> 16);
;                         tp[64] = (bf16_t)(w.z & 0xffff); tp[80] = (bf16_t)(w.z >> 16); tp[96] = (bf16_t)(w.w & 0xffff); tp[112] = (bf16_t)(w.w >> 16);
;                         asm volatile("s_waitcnt lgkmcnt(0)" ::: "memory");
;                         const u32x4 tv = *(const LAS u32x4*)(tw + (lane >> 1) * 32 + (lane & 1) * 16);
;                         asm volatile("s_waitcnt lgkmcnt(0)" ::: "memory");
;                         const int cc = (col - 8 * fq) - 2 * D + (lane >> 1), h = cc >> 6, d = cc & 63, t0 = (t - fr) + (lane & 1) * 8;
.LBB0_464:
	s_addk_i32 s30, 0x80
	s_nop 0
	v_or_b32_e32 v74, s30, v147
	s_movk_i32 s0, 0x7fff
	s_ashr_i32 s6, s30, 12
	v_cmp_lt_i32_e64 s[42:43], s0, v74
	v_add_u32_e32 v66, 0xffff8000, v74
	v_cmp_gt_i32_e64 s[0:1], s81, v74
	v_lshrrev_b32_e32 v64, 6, v66
	v_mov_b32_e32 v68, s6
	v_cndmask_b32_e64 v67, 15, v234, s[0:1]
	v_cndmask_b32_e64 v70, v64, v68, s[0:1]
	v_bitop3_b32 v64, v67, s30, v147 bitop3:0xe0
	v_ashrrev_i32_e32 v67, 31, v66
	v_lshlrev_b64 v[66:67], 10, v[66:67]
	v_ashrrev_i32_e32 v75, 31, v74
	v_add_u32_e32 v84, v64, v179
	v_add_u32_e32 v64, 0x800, v64
	v_lshl_add_u64 v[86:87], v[66:67], 0, s[70:71]
	v_lshlrev_b64 v[68:69], 10, v[74:75]
	v_lshl_add_u64 v[80:81], v[66:67], 0, s[74:75]
	v_mad_i64_i32 v[66:67], s[4:5], v70, s22, v[64:65]
	v_lshl_add_u64 v[88:89], v[68:69], 0, s[72:73]
	v_lshlrev_b32_e32 v94, 4, v70
	v_ashrrev_i32_e32 v85, 31, v84
	v_lshl_add_u64 v[82:83], v[68:69], 0, s[76:77]
	v_lshlrev_b64 v[76:77], 11, v[66:67]
	v_lshlrev_b64 v[78:79], 11, v[74:75]
	v_cvt_pk_bf16_f32 v66, v60, v61
	v_cvt_pk_bf16_f32 v67, v62, v63
	v_cvt_pk_bf16_f32 v68, v56, v57
	v_cvt_pk_bf16_f32 v69, v58, v59
	s_and_b64 vcc, exec, s[40:41]
	s_mov_b64 s[4:5], -1
	s_cbranch_vccnz .LBB0_474
	s_and_b64 vcc, exec, s[38:39]
	s_cbranch_vccnz .LBB0_471
	v_cndmask_b32_e64 v71, v87, v89, s[0:1]
	v_cndmask_b32_e64 v70, v86, v88, s[0:1]
	v_lshl_add_u64 v[70:71], v[70:71], 2, s[28:29]
	v_mov_b32_e32 v155, v65
	v_lshl_add_u64 v[70:71], v[154:155], 2, v[70:71]
	v_add_co_u32_e32 v72, vcc, 0xffffe000, v70
	v_add_u32_e32 v64, v181, v178
	s_nop 0
	v_addc_co_u32_e32 v73, vcc, -1, v71, vcc
	v_add_co_u32_e32 v70, vcc, 0xffffe010, v70
	global_store_dwordx4 v[72:73], v[60:63], off
	s_nop 0
	v_addc_co_u32_e32 v71, vcc, -1, v71, vcc
	global_store_dwordx4 v[70:71], v[56:59], off
	ds_write_b16 v180, v66
	ds_write_b16_d16_hi v180, v66 offset:32
	ds_write_b16 v180, v67 offset:64
	ds_write_b16_d16_hi v180, v67 offset:96
	ds_write_b16 v180, v68 offset:128
	ds_write_b16_d16_hi v180, v68 offset:160
	ds_write_b16 v180, v69 offset:192
	ds_write_b16_d16_hi v180, v69 offset:224
	s_waitcnt lgkmcnt(0)
	ds_read_b128 v[70:73], v64
	s_add_i32 s4, s26, 0xfffff800
	s_waitcnt lgkmcnt(0)
	s_ashr_i32 s4, s4, 6
	v_add_u32_e32 v92, s4, v94
	v_ashrrev_i32_e32 v93, 31, v92
	s_and_saveexec_b64 s[4:5], s[42:43]
	s_xor_b64 s[4:5], exec, s[4:5]
	v_lshlrev_b64 v[90:91], 6, v[92:93]
	v_or_b32_e32 v64, v90, v146
	v_mov_b64_e32 v[92:93], s[52:53]
	s_movk_i32 s7, 0x1080
	v_mad_u64_u32 v[92:93], s[10:11], v64, s7, v[92:93]
	v_mad_i32_i24 v93, v91, s7, v93
	v_lshl_add_u64 v[90:91], v[92:93], 0, s[96:97]
	s_andn2_saveexec_b64 s[4:5], s[4:5]
	v_lshlrev_b64 v[90:91], 19, v[92:93]
	v_lshl_add_u64 v[90:91], v[148:149], 0, v[90:91]
	s_or_b64 exec, exec, s[4:5]
	v_lshl_add_u64 v[90:91], v[84:85], 1, v[90:91]
	s_mov_b64 s[4:5], 0
	s_waitcnt lgkmcnt(0)
	global_store_dwordx4 v[90:91], v[70:73], off
.LBB0_471:
	s_and_b64 vcc, exec, s[4:5]
	s_cbranch_vccz .LBB0_473
	v_add_u32_e32 v70, 0xfffffc00, v154
	v_cndmask_b32_e64 v73, v81, v83, s[0:1]
	v_cndmask_b32_e64 v72, v80, v82, s[0:1]
	v_lshl_add_u64 v[72:73], v[72:73], 2, s[28:29]
	v_ashrrev_i32_e32 v71, 31, v70
	v_lshl_add_u64 v[72:73], v[70:71], 2, v[72:73]
	global_store_dwordx4 v[72:73], v[60:63], off
	global_store_dwordx4 v[72:73], v[56:59], off offset:16
	s_nop 1
	v_lshl_add_u64 v[56:57], s[50:51], 0, v[76:77]
	v_lshl_add_u64 v[58:59], s[48:49], 0, v[78:79]
	v_cndmask_b32_e64 v57, v57, v59, s[0:1]
	v_cndmask_b32_e64 v56, v56, v58, s[0:1]
	v_lshl_add_u64 v[56:57], v[70:71], 1, v[56:57]
	global_store_dwordx4 v[56:57], v[66:69], off

; #define LAS __attribute__((address_space(3)))
;     DI void operator()(const f32x4 (&acc)[2][2][4][2], const Unit& u, int wr, int wc, int fr, int fq) const {
;     ...
;                 const int row = u.pm * 256 + ai * 128 + wr * 64 + m * 16 + fr;
;                 int s, b, t; rowinfo(row, s, b, t);
; #pragma unroll
;                 for (int bj = 0; bj < 2; ++bj) {
;                     const int col = u.pn * 256 + bj * 128 + wc * 32 + 8 * fq;
;                     u32x4 w; w.x = pk2(acc[ai][bj][m][0][0], acc[ai][bj][m][0][1]); w.y = pk2(acc[ai][bj][m][0][2], acc[ai][bj][m][0][3]); w.z = pk2(acc[ai][bj][m][1][0], acc[ai][bj][m][1][1]); w.w = pk2(acc[ai][bj][m][1][2], acc[ai][bj][m][1][3]);
;                     if (u.pn < 4) { *(u32x4*)(Q + (size_t)row * D + col) = w; }
;                     else if (u.pn < 8) {
;                         const int c = col - D;
;                         float* o = out + (s ? O_KS + (size_t)(row - MP) * D : O_KP + (size_t)row * D) + c; __builtin_nontemporal_store(acc[ai][bj][m][0], (f32x4*)o); __builtin_nontemporal_store(acc[ai][bj][m][1], (f32x4*)(o + 4));
;                         bf16_t* kb = s ? KS + ((size_t)b * LK + PAST + t) * D + c : KP + (size_t)row * D + c; *(u32x4*)kb = w;
;                     } else {
;                         const int c = col - 2 * D;
;                         float* o = out + (s ? O_VS + (size_t)(row - MP) * D : O_VP + (size_t)row * D) + c; __builtin_nontemporal_store(acc[ai][bj][m][0], (f32x4*)o); __builtin_nontemporal_store(acc[ai][bj][m][1], (f32x4*)(o + 4));
;                         LAS bf16_t* tp = (LAS bf16_t*)tw + (8 * fq) * 16 + fr;
;                         tp[0] = (bf16_t)(w.x & 0xffff); tp[16] = (bf16_t)(w.x >> 16); tp[32] = (bf16_t)(w.y & 0xffff); tp[48] = (bf16_t)(w.y >> 16);
;                         tp[64] = (bf16_t)(w.z & 0xffff); tp[80] = (bf16_t)(w.z >> 16); tp[96] = (bf16_t)(w.w & 0xffff); tp[112] = (bf16_t)(w.w >> 16);
;                         asm volatile("s_waitcnt lgkmcnt(0)" ::: "memory");
;                         const u32x4 tv = *(const LAS u32x4*)(tw + (lane >> 1) * 32 + (lane & 1) * 16);
;                         asm volatile("s_waitcnt lgkmcnt(0)" ::: "memory");
;                         const int cc = (col - 8 * fq) - 2 * D + (lane >> 1), h = cc >> 6, d = cc & 63, t0 = (t - fr) + (lane & 1) * 8;
.LBB0_476:
	v_cvt_pk_bf16_f32 v56, v52, v53
	v_cvt_pk_bf16_f32 v57, v54, v55
	v_cvt_pk_bf16_f32 v58, v48, v49
	v_cvt_pk_bf16_f32 v59, v50, v51
	s_and_b64 vcc, exec, s[40:41]
	s_mov_b64 s[4:5], -1
	s_cbranch_vccnz .LBB0_486
	s_and_b64 vcc, exec, s[38:39]
	s_cbranch_vccnz .LBB0_483
	v_cndmask_b32_e64 v61, v87, v89, s[0:1]
	v_cndmask_b32_e64 v60, v86, v88, s[0:1]
	v_lshl_add_u64 v[60:61], v[60:61], 2, s[28:29]
	v_mov_b32_e32 v155, v65
	v_lshl_add_u64 v[60:61], v[154:155], 2, v[60:61]
	v_add_co_u32_e32 v62, vcc, 0xffffe200, v60
	s_add_i32 s4, s26, 0xfffff880
	s_nop 0
	v_addc_co_u32_e32 v63, vcc, -1, v61, vcc
	v_add_co_u32_e32 v60, vcc, 0xffffe210, v60
	global_store_dwordx4 v[62:63], v[52:55], off
	s_nop 0
	v_addc_co_u32_e32 v61, vcc, -1, v61, vcc
	global_store_dwordx4 v[60:61], v[48:51], off
	ds_write_b16 v180, v56
	ds_write_b16_d16_hi v180, v56 offset:32
	ds_write_b16 v180, v57 offset:64
	ds_write_b16_d16_hi v180, v57 offset:96
	ds_write_b16 v180, v58 offset:128
	ds_write_b16_d16_hi v180, v58 offset:160
	ds_write_b16 v180, v59 offset:192
	ds_write_b16_d16_hi v180, v59 offset:224
	s_waitcnt lgkmcnt(0)
	v_add_u32_e32 v60, v181, v178
	ds_read_b128 v[60:63], v60
	s_waitcnt lgkmcnt(0)
	s_ashr_i32 s4, s4, 6
	v_add_u32_e32 v68, s4, v94
	v_ashrrev_i32_e32 v69, 31, v68
	s_and_saveexec_b64 s[4:5], s[42:43]
	s_xor_b64 s[4:5], exec, s[4:5]
	v_lshlrev_b64 v[66:67], 6, v[68:69]
	v_or_b32_e32 v64, v66, v146
	v_mov_b64_e32 v[68:69], s[52:53]
	s_movk_i32 s7, 0x1080
	v_mad_u64_u32 v[68:69], s[10:11], v64, s7, v[68:69]
	v_mad_i32_i24 v69, v67, s7, v69
	v_lshl_add_u64 v[66:67], v[68:69], 0, s[96:97]
	s_andn2_saveexec_b64 s[4:5], s[4:5]
	v_lshlrev_b64 v[66:67], 19, v[68:69]
	v_lshl_add_u64 v[66:67], v[148:149], 0, v[66:67]
	s_or_b64 exec, exec, s[4:5]
	v_lshl_add_u64 v[66:67], v[84:85], 1, v[66:67]
	s_mov_b64 s[4:5], 0
	s_waitcnt lgkmcnt(0)
	global_store_dwordx4 v[66:67], v[60:63], off
.LBB0_483:
	s_and_b64 vcc, exec, s[4:5]
	s_cbranch_vccz .LBB0_485
	v_add_u32_e32 v60, 0xfffffc80, v154
	v_cndmask_b32_e64 v63, v81, v83, s[0:1]
	v_cndmask_b32_e64 v62, v80, v82, s[0:1]
	v_lshl_add_u64 v[62:63], v[62:63], 2, s[28:29]
	v_ashrrev_i32_e32 v61, 31, v60
	v_lshl_add_u64 v[62:63], v[60:61], 2, v[62:63]
	global_store_dwordx4 v[62:63], v[52:55], off
	global_store_dwordx4 v[62:63], v[48:51], off offset:16
	s_nop 1
	v_lshl_add_u64 v[48:49], s[50:51], 0, v[76:77]
	v_lshl_add_u64 v[50:51], s[48:49], 0, v[78:79]
	v_cndmask_b32_e64 v49, v49, v51, s[0:1]
	v_cndmask_b32_e64 v48, v48, v50, s[0:1]
	v_lshl_add_u64 v[48:49], v[60:61], 1, v[48:49]
	global_store_dwordx4 v[48:49], v[56:59], off

; #define LAS __attribute__((address_space(3)))
;     DI void operator()(const f32x4 (&acc)[2][2][4][2], const Unit& u, int wr, int wc, int fr, int fq) const {
;     ...
;                 const int row = u.pm * 256 + ai * 128 + wr * 64 + m * 16 + fr;
;                 int s, b, t; rowinfo(row, s, b, t);
; #pragma unroll
;                 for (int bj = 0; bj < 2; ++bj) {
;                     const int col = u.pn * 256 + bj * 128 + wc * 32 + 8 * fq;
;                     u32x4 w; w.x = pk2(acc[ai][bj][m][0][0], acc[ai][bj][m][0][1]); w.y = pk2(acc[ai][bj][m][0][2], acc[ai][bj][m][0][3]); w.z = pk2(acc[ai][bj][m][1][0], acc[ai][bj][m][1][1]); w.w = pk2(acc[ai][bj][m][1][2], acc[ai][bj][m][1][3]);
;                     if (u.pn < 4) { *(u32x4*)(Q + (size_t)row * D + col) = w; }
;                     else if (u.pn < 8) {
;                         const int c = col - D;
;                         float* o = out + (s ? O_KS + (size_t)(row - MP) * D : O_KP + (size_t)row * D) + c; __builtin_nontemporal_store(acc[ai][bj][m][0], (f32x4*)o); __builtin_nontemporal_store(acc[ai][bj][m][1], (f32x4*)(o + 4));
;                         bf16_t* kb = s ? KS + ((size_t)b * LK + PAST + t) * D + c : KP + (size_t)row * D + c; *(u32x4*)kb = w;
;                     } else {
;                         const int c = col - 2 * D;
;                         float* o = out + (s ? O_VS + (size_t)(row - MP) * D : O_VP + (size_t)row * D) + c; __builtin_nontemporal_store(acc[ai][bj][m][0], (f32x4*)o); __builtin_nontemporal_store(acc[ai][bj][m][1], (f32x4*)(o + 4));
;                         LAS bf16_t* tp = (LAS bf16_t*)tw + (8 * fq) * 16 + fr;
;                         tp[0] = (bf16_t)(w.x & 0xffff); tp[16] = (bf16_t)(w.x >> 16); tp[32] = (bf16_t)(w.y & 0xffff); tp[48] = (bf16_t)(w.y >> 16);
;                         tp[64] = (bf16_t)(w.z & 0xffff); tp[80] = (bf16_t)(w.z >> 16); tp[96] = (bf16_t)(w.w & 0xffff); tp[112] = (bf16_t)(w.w >> 16);
;                         asm volatile("s_waitcnt lgkmcnt(0)" ::: "memory");
;                         const u32x4 tv = *(const LAS u32x4*)(tw + (lane >> 1) * 32 + (lane & 1) * 16);
;                         asm volatile("s_waitcnt lgkmcnt(0)" ::: "memory");
;                         const int cc = (col - 8 * fq) - 2 * D + (lane >> 1), h = cc >> 6, d = cc & 63, t0 = (t - fr) + (lane & 1) * 8;
.LBB0_488:
	v_or_b32_e32 v48, 16, v74
	s_movk_i32 s0, 0x7fff
	v_cmp_lt_i32_e64 s[42:43], s0, v48
	v_cmp_gt_i32_e64 s[0:1], s81, v48
	v_add_u32_e32 v50, 0xffff8010, v74
	v_lshrrev_b32_e32 v49, 6, v50
	v_cndmask_b32_e64 v51, 31, v235, s[0:1]
	v_bitop3_b32 v55, v51, v74, 16 bitop3:0xe0
	v_ashrrev_i32_e32 v51, 31, v50
	v_mov_b32_e32 v52, s6
	v_lshlrev_b64 v[50:51], 10, v[50:51]
	v_cndmask_b32_e64 v54, v49, v52, s[0:1]
	v_lshl_add_u64 v[66:67], v[50:51], 0, s[70:71]
	v_ashrrev_i32_e32 v49, 31, v48
	v_lshl_add_u64 v[60:61], v[50:51], 0, s[74:75]
	v_add_u32_e32 v50, 0x800, v55
	v_mov_b32_e32 v51, v65
	v_lshlrev_b64 v[52:53], 10, v[48:49]
	v_mad_i64_i32 v[50:51], s[4:5], v54, s22, v[50:51]
	v_lshl_add_u64 v[68:69], v[52:53], 0, s[72:73]
	v_add_u32_e32 v64, v55, v179
	v_lshlrev_b32_e32 v75, 4, v54
	v_lshl_add_u64 v[62:63], v[52:53], 0, s[76:77]
	v_lshlrev_b64 v[56:57], 11, v[50:51]
	v_lshlrev_b64 v[58:59], 11, v[48:49]
	v_cvt_pk_bf16_f32 v48, v44, v45
	v_cvt_pk_bf16_f32 v49, v46, v47
	v_cvt_pk_bf16_f32 v50, v40, v41
	v_cvt_pk_bf16_f32 v51, v42, v43
	s_and_b64 vcc, exec, s[40:41]
	s_mov_b64 s[4:5], -1
	s_cbranch_vccnz .LBB0_498
	s_and_b64 vcc, exec, s[38:39]
	s_cbranch_vccnz .LBB0_495
	v_cndmask_b32_e64 v53, v67, v69, s[0:1]
	v_cndmask_b32_e64 v52, v66, v68, s[0:1]
	v_lshl_add_u64 v[52:53], v[52:53], 2, s[28:29]
	v_mov_b32_e32 v155, v65
	v_lshl_add_u64 v[52:53], v[154:155], 2, v[52:53]
	v_add_co_u32_e32 v54, vcc, 0xffffe000, v52
	s_add_i32 s4, s26, 0xfffff800
	s_nop 0
	v_addc_co_u32_e32 v55, vcc, -1, v53, vcc
	v_add_co_u32_e32 v52, vcc, 0xffffe010, v52
	global_store_dwordx4 v[54:55], v[44:47], off
	s_nop 0
	v_addc_co_u32_e32 v53, vcc, -1, v53, vcc
	global_store_dwordx4 v[52:53], v[40:43], off
	ds_write_b16 v180, v48
	ds_write_b16_d16_hi v180, v48 offset:32
	ds_write_b16 v180, v49 offset:64
	ds_write_b16_d16_hi v180, v49 offset:96
	ds_write_b16 v180, v50 offset:128
	ds_write_b16_d16_hi v180, v50 offset:160
	ds_write_b16 v180, v51 offset:192
	ds_write_b16_d16_hi v180, v51 offset:224
	s_waitcnt lgkmcnt(0)
	v_add_u32_e32 v52, v181, v178
	ds_read_b128 v[52:55], v52
	s_waitcnt lgkmcnt(0)
	s_ashr_i32 s4, s4, 6
	v_add_u32_e32 v72, s4, v75
	v_ashrrev_i32_e32 v73, 31, v72
	s_and_saveexec_b64 s[4:5], s[42:43]
	s_xor_b64 s[4:5], exec, s[4:5]
	v_lshlrev_b64 v[70:71], 6, v[72:73]
	v_or_b32_e32 v70, v70, v146
	v_mov_b64_e32 v[72:73], s[52:53]
	s_movk_i32 s7, 0x1080
	v_mad_u64_u32 v[72:73], s[10:11], v70, s7, v[72:73]
	v_mad_i32_i24 v73, v71, s7, v73
	v_lshl_add_u64 v[70:71], v[72:73], 0, s[96:97]
	s_andn2_saveexec_b64 s[4:5], s[4:5]
	v_lshlrev_b64 v[70:71], 19, v[72:73]
	v_lshl_add_u64 v[70:71], v[148:149], 0, v[70:71]
	s_or_b64 exec, exec, s[4:5]
	v_lshl_add_u64 v[70:71], v[64:65], 1, v[70:71]
	s_mov_b64 s[4:5], 0
	s_waitcnt lgkmcnt(0)
	global_store_dwordx4 v[70:71], v[52:55], off
.LBB0_495:
	s_and_b64 vcc, exec, s[4:5]
	s_cbranch_vccz .LBB0_497
	v_add_u32_e32 v52, 0xfffffc00, v154
	v_cndmask_b32_e64 v55, v61, v63, s[0:1]
	v_cndmask_b32_e64 v54, v60, v62, s[0:1]
	v_lshl_add_u64 v[54:55], v[54:55], 2, s[28:29]
	v_ashrrev_i32_e32 v53, 31, v52
	v_lshl_add_u64 v[54:55], v[52:53], 2, v[54:55]
	global_store_dwordx4 v[54:55], v[44:47], off
	global_store_dwordx4 v[54:55], v[40:43], off offset:16
	s_nop 1
	v_lshl_add_u64 v[40:41], s[50:51], 0, v[56:57]
	v_lshl_add_u64 v[42:43], s[48:49], 0, v[58:59]
	v_cndmask_b32_e64 v41, v41, v43, s[0:1]
	v_cndmask_b32_e64 v40, v40, v42, s[0:1]
	v_lshl_add_u64 v[40:41], v[52:53], 1, v[40:41]
	global_store_dwordx4 v[40:41], v[48:51], off

; #define LAS __attribute__((address_space(3)))
;     DI void operator()(const f32x4 (&acc)[2][2][4][2], const Unit& u, int wr, int wc, int fr, int fq) const {
;     ...
;                 const int row = u.pm * 256 + ai * 128 + wr * 64 + m * 16 + fr;
;                 int s, b, t; rowinfo(row, s, b, t);
; #pragma unroll
;                 for (int bj = 0; bj < 2; ++bj) {
;                     const int col = u.pn * 256 + bj * 128 + wc * 32 + 8 * fq;
;                     u32x4 w; w.x = pk2(acc[ai][bj][m][0][0], acc[ai][bj][m][0][1]); w.y = pk2(acc[ai][bj][m][0][2], acc[ai][bj][m][0][3]); w.z = pk2(acc[ai][bj][m][1][0], acc[ai][bj][m][1][1]); w.w = pk2(acc[ai][bj][m][1][2], acc[ai][bj][m][1][3]);
;                     if (u.pn < 4) { *(u32x4*)(Q + (size_t)row * D + col) = w; }
;                     else if (u.pn < 8) {
;                         const int c = col - D;
;                         float* o = out + (s ? O_KS + (size_t)(row - MP) * D : O_KP + (size_t)row * D) + c; __builtin_nontemporal_store(acc[ai][bj][m][0], (f32x4*)o); __builtin_nontemporal_store(acc[ai][bj][m][1], (f32x4*)(o + 4));
;                         bf16_t* kb = s ? KS + ((size_t)b * LK + PAST + t) * D + c : KP + (size_t)row * D + c; *(u32x4*)kb = w;
;                     } else {
;                         const int c = col - 2 * D;
;                         float* o = out + (s ? O_VS + (size_t)(row - MP) * D : O_VP + (size_t)row * D) + c; __builtin_nontemporal_store(acc[ai][bj][m][0], (f32x4*)o); __builtin_nontemporal_store(acc[ai][bj][m][1], (f32x4*)(o + 4));
;                         LAS bf16_t* tp = (LAS bf16_t*)tw + (8 * fq) * 16 + fr;
;                         tp[0] = (bf16_t)(w.x & 0xffff); tp[16] = (bf16_t)(w.x >> 16); tp[32] = (bf16_t)(w.y & 0xffff); tp[48] = (bf16_t)(w.y >> 16);
;                         tp[64] = (bf16_t)(w.z & 0xffff); tp[80] = (bf16_t)(w.z >> 16); tp[96] = (bf16_t)(w.w & 0xffff); tp[112] = (bf16_t)(w.w >> 16);
;                         asm volatile("s_waitcnt lgkmcnt(0)" ::: "memory");
;                         const u32x4 tv = *(const LAS u32x4*)(tw + (lane >> 1) * 32 + (lane & 1) * 16);
;                         asm volatile("s_waitcnt lgkmcnt(0)" ::: "memory");
;                         const int cc = (col - 8 * fq) - 2 * D + (lane >> 1), h = cc >> 6, d = cc & 63, t0 = (t - fr) + (lane & 1) * 8;
.LBB0_500:
	v_cvt_pk_bf16_f32 v40, v36, v37
	v_cvt_pk_bf16_f32 v41, v38, v39
	v_cvt_pk_bf16_f32 v42, v32, v33
	v_cvt_pk_bf16_f32 v43, v34, v35
	s_and_b64 vcc, exec, s[40:41]
	s_mov_b64 s[4:5], -1
	s_cbranch_vccnz .LBB0_510
	s_and_b64 vcc, exec, s[38:39]
	s_cbranch_vccnz .LBB0_507
	v_cndmask_b32_e64 v45, v67, v69, s[0:1]
	v_cndmask_b32_e64 v44, v66, v68, s[0:1]
	v_lshl_add_u64 v[44:45], v[44:45], 2, s[28:29]
	v_mov_b32_e32 v155, v65
	v_lshl_add_u64 v[44:45], v[154:155], 2, v[44:45]
	v_add_co_u32_e32 v46, vcc, 0xffffe200, v44
	s_add_i32 s4, s26, 0xfffff880
	s_nop 0
	v_addc_co_u32_e32 v47, vcc, -1, v45, vcc
	v_add_co_u32_e32 v44, vcc, 0xffffe210, v44
	global_store_dwordx4 v[46:47], v[36:39], off
	s_nop 0
	v_addc_co_u32_e32 v45, vcc, -1, v45, vcc
	global_store_dwordx4 v[44:45], v[32:35], off
	ds_write_b16 v180, v40
	ds_write_b16_d16_hi v180, v40 offset:32
	ds_write_b16 v180, v41 offset:64
	ds_write_b16_d16_hi v180, v41 offset:96
	ds_write_b16 v180, v42 offset:128
	ds_write_b16_d16_hi v180, v42 offset:160
	ds_write_b16 v180, v43 offset:192
	ds_write_b16_d16_hi v180, v43 offset:224
	s_waitcnt lgkmcnt(0)
	v_add_u32_e32 v44, v181, v178
	ds_read_b128 v[44:47], v44
	s_waitcnt lgkmcnt(0)
	s_ashr_i32 s4, s4, 6
	v_add_u32_e32 v50, s4, v75
	v_ashrrev_i32_e32 v51, 31, v50
	s_and_saveexec_b64 s[4:5], s[42:43]
	s_xor_b64 s[4:5], exec, s[4:5]
	v_lshlrev_b64 v[48:49], 6, v[50:51]
	v_or_b32_e32 v48, v48, v146
	v_mov_b64_e32 v[50:51], s[52:53]
	s_movk_i32 s7, 0x1080
	v_mad_u64_u32 v[50:51], s[10:11], v48, s7, v[50:51]
	v_mad_i32_i24 v51, v49, s7, v51
	v_lshl_add_u64 v[48:49], v[50:51], 0, s[96:97]
	s_andn2_saveexec_b64 s[4:5], s[4:5]
	v_lshlrev_b64 v[48:49], 19, v[50:51]
	v_lshl_add_u64 v[48:49], v[148:149], 0, v[48:49]
	s_or_b64 exec, exec, s[4:5]
	v_lshl_add_u64 v[48:49], v[64:65], 1, v[48:49]
	s_mov_b64 s[4:5], 0
	s_waitcnt lgkmcnt(0)
	global_store_dwordx4 v[48:49], v[44:47], off
.LBB0_507:
	s_and_b64 vcc, exec, s[4:5]
	s_cbranch_vccz .LBB0_509
	v_add_u32_e32 v44, 0xfffffc80, v154
	v_cndmask_b32_e64 v47, v61, v63, s[0:1]
	v_cndmask_b32_e64 v46, v60, v62, s[0:1]
	v_lshl_add_u64 v[46:47], v[46:47], 2, s[28:29]
	v_ashrrev_i32_e32 v45, 31, v44
	v_lshl_add_u64 v[46:47], v[44:45], 2, v[46:47]
	global_store_dwordx4 v[46:47], v[36:39], off
	global_store_dwordx4 v[46:47], v[32:35], off offset:16
	s_nop 1
	v_lshl_add_u64 v[32:33], s[50:51], 0, v[56:57]
	v_lshl_add_u64 v[34:35], s[48:49], 0, v[58:59]
	v_cndmask_b32_e64 v33, v33, v35, s[0:1]
	v_cndmask_b32_e64 v32, v32, v34, s[0:1]
	v_lshl_add_u64 v[32:33], v[44:45], 1, v[32:33]
	global_store_dwordx4 v[32:33], v[40:43], off

; #define LAS __attribute__((address_space(3)))
;     DI void operator()(const f32x4 (&acc)[2][2][4][2], const Unit& u, int wr, int wc, int fr, int fq) const {
;     ...
;                 const int row = u.pm * 256 + ai * 128 + wr * 64 + m * 16 + fr;
;                 int s, b, t; rowinfo(row, s, b, t);
; #pragma unroll
;                 for (int bj = 0; bj < 2; ++bj) {
;                     const int col = u.pn * 256 + bj * 128 + wc * 32 + 8 * fq;
;                     u32x4 w; w.x = pk2(acc[ai][bj][m][0][0], acc[ai][bj][m][0][1]); w.y = pk2(acc[ai][bj][m][0][2], acc[ai][bj][m][0][3]); w.z = pk2(acc[ai][bj][m][1][0], acc[ai][bj][m][1][1]); w.w = pk2(acc[ai][bj][m][1][2], acc[ai][bj][m][1][3]);
;                     if (u.pn < 4) { *(u32x4*)(Q + (size_t)row * D + col) = w; }
;                     else if (u.pn < 8) {
;                         const int c = col - D;
;                         float* o = out + (s ? O_KS + (size_t)(row - MP) * D : O_KP + (size_t)row * D) + c; __builtin_nontemporal_store(acc[ai][bj][m][0], (f32x4*)o); __builtin_nontemporal_store(acc[ai][bj][m][1], (f32x4*)(o + 4));
;                         bf16_t* kb = s ? KS + ((size_t)b * LK + PAST + t) * D + c : KP + (size_t)row * D + c; *(u32x4*)kb = w;
;                     } else {
;                         const int c = col - 2 * D;
;                         float* o = out + (s ? O_VS + (size_t)(row - MP) * D : O_VP + (size_t)row * D) + c; __builtin_nontemporal_store(acc[ai][bj][m][0], (f32x4*)o); __builtin_nontemporal_store(acc[ai][bj][m][1], (f32x4*)(o + 4));
;                         LAS bf16_t* tp = (LAS bf16_t*)tw + (8 * fq) * 16 + fr;
;                         tp[0] = (bf16_t)(w.x & 0xffff); tp[16] = (bf16_t)(w.x >> 16); tp[32] = (bf16_t)(w.y & 0xffff); tp[48] = (bf16_t)(w.y >> 16);
;                         tp[64] = (bf16_t)(w.z & 0xffff); tp[80] = (bf16_t)(w.z >> 16); tp[96] = (bf16_t)(w.w & 0xffff); tp[112] = (bf16_t)(w.w >> 16);
;                         asm volatile("s_waitcnt lgkmcnt(0)" ::: "memory");
;                         const u32x4 tv = *(const LAS u32x4*)(tw + (lane >> 1) * 32 + (lane & 1) * 16);
;                         asm volatile("s_waitcnt lgkmcnt(0)" ::: "memory");
;                         const int cc = (col - 8 * fq) - 2 * D + (lane >> 1), h = cc >> 6, d = cc & 63, t0 = (t - fr) + (lane & 1) * 8;
.LBB0_512:
	v_or_b32_e32 v32, 32, v74
	s_movk_i32 s0, 0x7fff
	v_cmp_lt_i32_e64 s[42:43], s0, v32
	v_cmp_gt_i32_e64 s[0:1], s81, v32
	v_add_u32_e32 v34, 0xffff8020, v74
	v_lshrrev_b32_e32 v33, 6, v34
	v_cndmask_b32_e64 v35, 47, v236, s[0:1]
	v_bitop3_b32 v39, v35, v74, 32 bitop3:0xe0
	v_ashrrev_i32_e32 v35, 31, v34
	v_mov_b32_e32 v36, s6
	v_lshlrev_b64 v[34:35], 10, v[34:35]
	v_cndmask_b32_e64 v38, v33, v36, s[0:1]
	v_lshl_add_u64 v[48:49], v[34:35], 0, s[70:71]
	v_ashrrev_i32_e32 v33, 31, v32
	v_lshl_add_u64 v[44:45], v[34:35], 0, s[74:75]
	v_add_u32_e32 v34, 0x800, v39
	v_mov_b32_e32 v35, v65
	v_lshlrev_b64 v[36:37], 10, v[32:33]
	v_mad_i64_i32 v[34:35], s[4:5], v38, s22, v[34:35]
	v_lshl_add_u64 v[50:51], v[36:37], 0, s[72:73]
	v_add_u32_e32 v64, v39, v179
	v_lshlrev_b32_e32 v56, 4, v38
	v_lshl_add_u64 v[46:47], v[36:37], 0, s[76:77]
	v_lshlrev_b64 v[40:41], 11, v[34:35]
	v_lshlrev_b64 v[42:43], 11, v[32:33]
	v_cvt_pk_bf16_f32 v32, v28, v29
	v_cvt_pk_bf16_f32 v33, v30, v31
	v_cvt_pk_bf16_f32 v34, v24, v25
	v_cvt_pk_bf16_f32 v35, v26, v27
	s_and_b64 vcc, exec, s[40:41]
	s_mov_b64 s[4:5], -1
	s_cbranch_vccnz .LBB0_522
	s_and_b64 vcc, exec, s[38:39]
	s_cbranch_vccnz .LBB0_519
	v_cndmask_b32_e64 v37, v49, v51, s[0:1]
	v_cndmask_b32_e64 v36, v48, v50, s[0:1]
	v_lshl_add_u64 v[36:37], v[36:37], 2, s[28:29]
	v_mov_b32_e32 v155, v65
	v_lshl_add_u64 v[36:37], v[154:155], 2, v[36:37]
	v_add_co_u32_e32 v38, vcc, 0xffffe000, v36
	s_add_i32 s4, s26, 0xfffff800
	s_nop 0
	v_addc_co_u32_e32 v39, vcc, -1, v37, vcc
	v_add_co_u32_e32 v36, vcc, 0xffffe010, v36
	global_store_dwordx4 v[38:39], v[28:31], off
	s_nop 0
	v_addc_co_u32_e32 v37, vcc, -1, v37, vcc
	global_store_dwordx4 v[36:37], v[24:27], off
	ds_write_b16 v180, v32
	ds_write_b16_d16_hi v180, v32 offset:32
	ds_write_b16 v180, v33 offset:64
	ds_write_b16_d16_hi v180, v33 offset:96
	ds_write_b16 v180, v34 offset:128
	ds_write_b16_d16_hi v180, v34 offset:160
	ds_write_b16 v180, v35 offset:192
	ds_write_b16_d16_hi v180, v35 offset:224
	s_waitcnt lgkmcnt(0)
	v_add_u32_e32 v36, v181, v178
	ds_read_b128 v[36:39], v36
	s_waitcnt lgkmcnt(0)
	s_ashr_i32 s4, s4, 6
	v_add_u32_e32 v54, s4, v56
	v_ashrrev_i32_e32 v55, 31, v54
	s_and_saveexec_b64 s[4:5], s[42:43]
	s_xor_b64 s[4:5], exec, s[4:5]
	v_lshlrev_b64 v[52:53], 6, v[54:55]
	v_or_b32_e32 v52, v52, v146
	v_mov_b64_e32 v[54:55], s[52:53]
	s_movk_i32 s7, 0x1080
	v_mad_u64_u32 v[54:55], s[10:11], v52, s7, v[54:55]
	v_mad_i32_i24 v55, v53, s7, v55
	v_lshl_add_u64 v[52:53], v[54:55], 0, s[96:97]
	s_andn2_saveexec_b64 s[4:5], s[4:5]
	v_lshlrev_b64 v[52:53], 19, v[54:55]
	v_lshl_add_u64 v[52:53], v[148:149], 0, v[52:53]
	s_or_b64 exec, exec, s[4:5]
	v_lshl_add_u64 v[52:53], v[64:65], 1, v[52:53]
	s_mov_b64 s[4:5], 0
	s_waitcnt lgkmcnt(0)
	global_store_dwordx4 v[52:53], v[36:39], off
.LBB0_519:
	s_and_b64 vcc, exec, s[4:5]
	s_cbranch_vccz .LBB0_521
	v_add_u32_e32 v36, 0xfffffc00, v154
	v_cndmask_b32_e64 v39, v45, v47, s[0:1]
	v_cndmask_b32_e64 v38, v44, v46, s[0:1]
	v_lshl_add_u64 v[38:39], v[38:39], 2, s[28:29]
	v_ashrrev_i32_e32 v37, 31, v36
	v_lshl_add_u64 v[38:39], v[36:37], 2, v[38:39]
	global_store_dwordx4 v[38:39], v[28:31], off
	global_store_dwordx4 v[38:39], v[24:27], off offset:16
	s_nop 1
	v_lshl_add_u64 v[24:25], s[50:51], 0, v[40:41]
	v_lshl_add_u64 v[26:27], s[48:49], 0, v[42:43]
	v_cndmask_b32_e64 v25, v25, v27, s[0:1]
	v_cndmask_b32_e64 v24, v24, v26, s[0:1]
	v_lshl_add_u64 v[24:25], v[36:37], 1, v[24:25]
	global_store_dwordx4 v[24:25], v[32:35], off

; #define LAS __attribute__((address_space(3)))
;     DI void operator()(const f32x4 (&acc)[2][2][4][2], const Unit& u, int wr, int wc, int fr, int fq) const {
;     ...
;                 const int row = u.pm * 256 + ai * 128 + wr * 64 + m * 16 + fr;
;                 int s, b, t; rowinfo(row, s, b, t);
; #pragma unroll
;                 for (int bj = 0; bj < 2; ++bj) {
;                     const int col = u.pn * 256 + bj * 128 + wc * 32 + 8 * fq;
;                     u32x4 w; w.x = pk2(acc[ai][bj][m][0][0], acc[ai][bj][m][0][1]); w.y = pk2(acc[ai][bj][m][0][2], acc[ai][bj][m][0][3]); w.z = pk2(acc[ai][bj][m][1][0], acc[ai][bj][m][1][1]); w.w = pk2(acc[ai][bj][m][1][2], acc[ai][bj][m][1][3]);
;                     if (u.pn < 4) { *(u32x4*)(Q + (size_t)row * D + col) = w; }
;                     else if (u.pn < 8) {
;                         const int c = col - D;
;                         float* o = out + (s ? O_KS + (size_t)(row - MP) * D : O_KP + (size_t)row * D) + c; __builtin_nontemporal_store(acc[ai][bj][m][0], (f32x4*)o); __builtin_nontemporal_store(acc[ai][bj][m][1], (f32x4*)(o + 4));
;                         bf16_t* kb = s ? KS + ((size_t)b * LK + PAST + t) * D + c : KP + (size_t)row * D + c; *(u32x4*)kb = w;
;                     } else {
;                         const int c = col - 2 * D;
;                         float* o = out + (s ? O_VS + (size_t)(row - MP) * D : O_VP + (size_t)row * D) + c; __builtin_nontemporal_store(acc[ai][bj][m][0], (f32x4*)o); __builtin_nontemporal_store(acc[ai][bj][m][1], (f32x4*)(o + 4));
;                         LAS bf16_t* tp = (LAS bf16_t*)tw + (8 * fq) * 16 + fr;
;                         tp[0] = (bf16_t)(w.x & 0xffff); tp[16] = (bf16_t)(w.x >> 16); tp[32] = (bf16_t)(w.y & 0xffff); tp[48] = (bf16_t)(w.y >> 16);
;                         tp[64] = (bf16_t)(w.z & 0xffff); tp[80] = (bf16_t)(w.z >> 16); tp[96] = (bf16_t)(w.w & 0xffff); tp[112] = (bf16_t)(w.w >> 16);
;                         asm volatile("s_waitcnt lgkmcnt(0)" ::: "memory");
;                         const u32x4 tv = *(const LAS u32x4*)(tw + (lane >> 1) * 32 + (lane & 1) * 16);
;                         asm volatile("s_waitcnt lgkmcnt(0)" ::: "memory");
;                         const int cc = (col - 8 * fq) - 2 * D + (lane >> 1), h = cc >> 6, d = cc & 63, t0 = (t - fr) + (lane & 1) * 8;
.LBB0_524:
	v_cvt_pk_bf16_f32 v24, v20, v21
	v_cvt_pk_bf16_f32 v25, v22, v23
	v_cvt_pk_bf16_f32 v26, v16, v17
	v_cvt_pk_bf16_f32 v27, v18, v19
	s_and_b64 vcc, exec, s[40:41]
	s_mov_b64 s[4:5], -1
	s_cbranch_vccnz .LBB0_534
	s_and_b64 vcc, exec, s[38:39]
	s_cbranch_vccnz .LBB0_531
	v_cndmask_b32_e64 v29, v49, v51, s[0:1]
	v_cndmask_b32_e64 v28, v48, v50, s[0:1]
	v_lshl_add_u64 v[28:29], v[28:29], 2, s[28:29]
	v_mov_b32_e32 v155, v65
	v_lshl_add_u64 v[28:29], v[154:155], 2, v[28:29]
	v_add_co_u32_e32 v30, vcc, 0xffffe200, v28
	s_add_i32 s4, s26, 0xfffff880
	s_nop 0
	v_addc_co_u32_e32 v31, vcc, -1, v29, vcc
	v_add_co_u32_e32 v28, vcc, 0xffffe210, v28
	global_store_dwordx4 v[30:31], v[20:23], off
	s_nop 0
	v_addc_co_u32_e32 v29, vcc, -1, v29, vcc
	global_store_dwordx4 v[28:29], v[16:19], off
	ds_write_b16 v180, v24
	ds_write_b16_d16_hi v180, v24 offset:32
	ds_write_b16 v180, v25 offset:64
	ds_write_b16_d16_hi v180, v25 offset:96
	ds_write_b16 v180, v26 offset:128
	ds_write_b16_d16_hi v180, v26 offset:160
	ds_write_b16 v180, v27 offset:192
	ds_write_b16_d16_hi v180, v27 offset:224
	s_waitcnt lgkmcnt(0)
	v_add_u32_e32 v28, v181, v178
	ds_read_b128 v[28:31], v28
	s_waitcnt lgkmcnt(0)
	s_ashr_i32 s4, s4, 6
	v_add_u32_e32 v34, s4, v56
	v_ashrrev_i32_e32 v35, 31, v34
	s_and_saveexec_b64 s[4:5], s[42:43]
	s_xor_b64 s[4:5], exec, s[4:5]
	v_lshlrev_b64 v[32:33], 6, v[34:35]
	v_or_b32_e32 v32, v32, v146
	v_mov_b64_e32 v[34:35], s[52:53]
	s_movk_i32 s7, 0x1080
	v_mad_u64_u32 v[34:35], s[10:11], v32, s7, v[34:35]
	v_mad_i32_i24 v35, v33, s7, v35
	v_lshl_add_u64 v[32:33], v[34:35], 0, s[96:97]
	s_andn2_saveexec_b64 s[4:5], s[4:5]
	v_lshlrev_b64 v[32:33], 19, v[34:35]
	v_lshl_add_u64 v[32:33], v[148:149], 0, v[32:33]
	s_or_b64 exec, exec, s[4:5]
	v_lshl_add_u64 v[32:33], v[64:65], 1, v[32:33]
	s_mov_b64 s[4:5], 0
	s_waitcnt lgkmcnt(0)
	global_store_dwordx4 v[32:33], v[28:31], off
.LBB0_531:
	s_and_b64 vcc, exec, s[4:5]
	s_cbranch_vccz .LBB0_533
	v_add_u32_e32 v28, 0xfffffc80, v154
	v_cndmask_b32_e64 v31, v45, v47, s[0:1]
	v_cndmask_b32_e64 v30, v44, v46, s[0:1]
	v_lshl_add_u64 v[30:31], v[30:31], 2, s[28:29]
	v_ashrrev_i32_e32 v29, 31, v28
	v_lshl_add_u64 v[30:31], v[28:29], 2, v[30:31]
	global_store_dwordx4 v[30:31], v[20:23], off
	global_store_dwordx4 v[30:31], v[16:19], off offset:16
	s_nop 1
	v_lshl_add_u64 v[16:17], s[50:51], 0, v[40:41]
	v_lshl_add_u64 v[18:19], s[48:49], 0, v[42:43]
	v_cndmask_b32_e64 v17, v17, v19, s[0:1]
	v_cndmask_b32_e64 v16, v16, v18, s[0:1]
	v_lshl_add_u64 v[16:17], v[28:29], 1, v[16:17]
	global_store_dwordx4 v[16:17], v[24:27], off

; #define LAS __attribute__((address_space(3)))
;     DI void operator()(const f32x4 (&acc)[2][2][4][2], const Unit& u, int wr, int wc, int fr, int fq) const {
;     ...
;                 const int row = u.pm * 256 + ai * 128 + wr * 64 + m * 16 + fr;
;                 int s, b, t; rowinfo(row, s, b, t);
; #pragma unroll
;                 for (int bj = 0; bj < 2; ++bj) {
;                     const int col = u.pn * 256 + bj * 128 + wc * 32 + 8 * fq;
;                     u32x4 w; w.x = pk2(acc[ai][bj][m][0][0], acc[ai][bj][m][0][1]); w.y = pk2(acc[ai][bj][m][0][2], acc[ai][bj][m][0][3]); w.z = pk2(acc[ai][bj][m][1][0], acc[ai][bj][m][1][1]); w.w = pk2(acc[ai][bj][m][1][2], acc[ai][bj][m][1][3]);
;                     if (u.pn < 4) { *(u32x4*)(Q + (size_t)row * D + col) = w; }
;                     else if (u.pn < 8) {
;                         const int c = col - D;
;                         float* o = out + (s ? O_KS + (size_t)(row - MP) * D : O_KP + (size_t)row * D) + c; __builtin_nontemporal_store(acc[ai][bj][m][0], (f32x4*)o); __builtin_nontemporal_store(acc[ai][bj][m][1], (f32x4*)(o + 4));
;                         bf16_t* kb = s ? KS + ((size_t)b * LK + PAST + t) * D + c : KP + (size_t)row * D + c; *(u32x4*)kb = w;
;                     } else {
;                         const int c = col - 2 * D;
;                         float* o = out + (s ? O_VS + (size_t)(row - MP) * D : O_VP + (size_t)row * D) + c; __builtin_nontemporal_store(acc[ai][bj][m][0], (f32x4*)o); __builtin_nontemporal_store(acc[ai][bj][m][1], (f32x4*)(o + 4));
;                         LAS bf16_t* tp = (LAS bf16_t*)tw + (8 * fq) * 16 + fr;
;                         tp[0] = (bf16_t)(w.x & 0xffff); tp[16] = (bf16_t)(w.x >> 16); tp[32] = (bf16_t)(w.y & 0xffff); tp[48] = (bf16_t)(w.y >> 16);
;                         tp[64] = (bf16_t)(w.z & 0xffff); tp[80] = (bf16_t)(w.z >> 16); tp[96] = (bf16_t)(w.w & 0xffff); tp[112] = (bf16_t)(w.w >> 16);
;                         asm volatile("s_waitcnt lgkmcnt(0)" ::: "memory");
;                         const u32x4 tv = *(const LAS u32x4*)(tw + (lane >> 1) * 32 + (lane & 1) * 16);
;                         asm volatile("s_waitcnt lgkmcnt(0)" ::: "memory");
;                         const int cc = (col - 8 * fq) - 2 * D + (lane >> 1), h = cc >> 6, d = cc & 63, t0 = (t - fr) + (lane & 1) * 8;
.LBB0_536:
	v_or_b32_e32 v16, 48, v74
	s_movk_i32 s0, 0x7fff
	v_cmp_lt_i32_e64 s[42:43], s0, v16
	v_cmp_gt_i32_e64 s[0:1], s81, v16
	v_add_u32_e32 v18, 0xffff8030, v74
	v_lshrrev_b32_e32 v17, 6, v18
	v_cndmask_b32_e64 v19, 63, v229, s[0:1]
	v_bitop3_b32 v23, v19, v74, 48 bitop3:0xe0
	v_ashrrev_i32_e32 v19, 31, v18
	v_mov_b32_e32 v20, s6
	v_lshlrev_b64 v[18:19], 10, v[18:19]
	v_cndmask_b32_e64 v22, v17, v20, s[0:1]
	v_lshl_add_u64 v[32:33], v[18:19], 0, s[70:71]
	v_ashrrev_i32_e32 v17, 31, v16
	v_lshl_add_u64 v[28:29], v[18:19], 0, s[74:75]
	v_add_u32_e32 v18, 0x800, v23
	v_mov_b32_e32 v19, v65
	v_lshlrev_b64 v[20:21], 10, v[16:17]
	v_mad_i64_i32 v[18:19], s[4:5], v22, s22, v[18:19]
	v_lshl_add_u64 v[34:35], v[20:21], 0, s[72:73]
	v_add_u32_e32 v64, v23, v179
	v_lshlrev_b32_e32 v40, 4, v22
	v_lshl_add_u64 v[30:31], v[20:21], 0, s[76:77]
	v_lshlrev_b64 v[24:25], 11, v[18:19]
	v_lshlrev_b64 v[26:27], 11, v[16:17]
	v_cvt_pk_bf16_f32 v16, v12, v13
	v_cvt_pk_bf16_f32 v17, v14, v15
	v_cvt_pk_bf16_f32 v18, v8, v9
	v_cvt_pk_bf16_f32 v19, v10, v11
	s_and_b64 vcc, exec, s[40:41]
	s_mov_b64 s[4:5], -1
	s_cbranch_vccnz .LBB0_546
	s_and_b64 vcc, exec, s[38:39]
	s_cbranch_vccnz .LBB0_543
	v_cndmask_b32_e64 v21, v33, v35, s[0:1]
	v_cndmask_b32_e64 v20, v32, v34, s[0:1]
	v_lshl_add_u64 v[20:21], v[20:21], 2, s[28:29]
	v_mov_b32_e32 v155, v65
	v_lshl_add_u64 v[20:21], v[154:155], 2, v[20:21]
	v_add_co_u32_e32 v22, vcc, 0xffffe000, v20
	s_add_i32 s4, s26, 0xfffff800
	s_nop 0
	v_addc_co_u32_e32 v23, vcc, -1, v21, vcc
	v_add_co_u32_e32 v20, vcc, 0xffffe010, v20
	global_store_dwordx4 v[22:23], v[12:15], off
	s_nop 0
	v_addc_co_u32_e32 v21, vcc, -1, v21, vcc
	global_store_dwordx4 v[20:21], v[8:11], off
	ds_write_b16 v180, v16
	ds_write_b16_d16_hi v180, v16 offset:32
	ds_write_b16 v180, v17 offset:64
	ds_write_b16_d16_hi v180, v17 offset:96
	ds_write_b16 v180, v18 offset:128
	ds_write_b16_d16_hi v180, v18 offset:160
	ds_write_b16 v180, v19 offset:192
	ds_write_b16_d16_hi v180, v19 offset:224
	s_waitcnt lgkmcnt(0)
	v_add_u32_e32 v20, v181, v178
	ds_read_b128 v[20:23], v20
	s_waitcnt lgkmcnt(0)
	s_ashr_i32 s4, s4, 6
	v_add_u32_e32 v38, s4, v40
	v_ashrrev_i32_e32 v39, 31, v38
	s_and_saveexec_b64 s[4:5], s[42:43]
	s_xor_b64 s[4:5], exec, s[4:5]
	v_lshlrev_b64 v[36:37], 6, v[38:39]
	v_or_b32_e32 v36, v36, v146
	v_mov_b64_e32 v[38:39], s[52:53]
	s_movk_i32 s10, 0x1080
	v_mad_u64_u32 v[38:39], s[6:7], v36, s10, v[38:39]
	v_mad_i32_i24 v39, v37, s10, v39
	v_lshl_add_u64 v[36:37], v[38:39], 0, s[96:97]
	s_andn2_saveexec_b64 s[4:5], s[4:5]
	v_lshlrev_b64 v[36:37], 19, v[38:39]
	v_lshl_add_u64 v[36:37], v[148:149], 0, v[36:37]
	s_or_b64 exec, exec, s[4:5]
	v_lshl_add_u64 v[36:37], v[64:65], 1, v[36:37]
	s_mov_b64 s[4:5], 0
	s_waitcnt lgkmcnt(0)
	global_store_dwordx4 v[36:37], v[20:23], off
.LBB0_543:
	s_and_b64 vcc, exec, s[4:5]
	s_cbranch_vccz .LBB0_545
	v_add_u32_e32 v20, 0xfffffc00, v154
	v_cndmask_b32_e64 v23, v29, v31, s[0:1]
	v_cndmask_b32_e64 v22, v28, v30, s[0:1]
	v_lshl_add_u64 v[22:23], v[22:23], 2, s[28:29]
	v_ashrrev_i32_e32 v21, 31, v20
	v_lshl_add_u64 v[22:23], v[20:21], 2, v[22:23]
	global_store_dwordx4 v[22:23], v[12:15], off
	global_store_dwordx4 v[22:23], v[8:11], off offset:16
	s_nop 1
	v_lshl_add_u64 v[8:9], s[50:51], 0, v[24:25]
	v_lshl_add_u64 v[10:11], s[48:49], 0, v[26:27]
	v_cndmask_b32_e64 v9, v9, v11, s[0:1]
	v_cndmask_b32_e64 v8, v8, v10, s[0:1]
	v_lshl_add_u64 v[8:9], v[20:21], 1, v[8:9]
	global_store_dwordx4 v[8:9], v[16:19], off

; #define LAS __attribute__((address_space(3)))
;     DI void operator()(const f32x4 (&acc)[2][2][4][2], const Unit& u, int wr, int wc, int fr, int fq) const {
;     ...
;                 const int row = u.pm * 256 + ai * 128 + wr * 64 + m * 16 + fr;
;                 int s, b, t; rowinfo(row, s, b, t);
; #pragma unroll
;                 for (int bj = 0; bj < 2; ++bj) {
;                     const int col = u.pn * 256 + bj * 128 + wc * 32 + 8 * fq;
;                     u32x4 w; w.x = pk2(acc[ai][bj][m][0][0], acc[ai][bj][m][0][1]); w.y = pk2(acc[ai][bj][m][0][2], acc[ai][bj][m][0][3]); w.z = pk2(acc[ai][bj][m][1][0], acc[ai][bj][m][1][1]); w.w = pk2(acc[ai][bj][m][1][2], acc[ai][bj][m][1][3]);
;                     if (u.pn < 4) { *(u32x4*)(Q + (size_t)row * D + col) = w; }
;                     else if (u.pn < 8) {
;                         const int c = col - D;
;                         float* o = out + (s ? O_KS + (size_t)(row - MP) * D : O_KP + (size_t)row * D) + c; __builtin_nontemporal_store(acc[ai][bj][m][0], (f32x4*)o); __builtin_nontemporal_store(acc[ai][bj][m][1], (f32x4*)(o + 4));
;                         bf16_t* kb = s ? KS + ((size_t)b * LK + PAST + t) * D + c : KP + (size_t)row * D + c; *(u32x4*)kb = w;
;                     } else {
;                         const int c = col - 2 * D;
;                         float* o = out + (s ? O_VS + (size_t)(row - MP) * D : O_VP + (size_t)row * D) + c; __builtin_nontemporal_store(acc[ai][bj][m][0], (f32x4*)o); __builtin_nontemporal_store(acc[ai][bj][m][1], (f32x4*)(o + 4));
;                         LAS bf16_t* tp = (LAS bf16_t*)tw + (8 * fq) * 16 + fr;
;                         tp[0] = (bf16_t)(w.x & 0xffff); tp[16] = (bf16_t)(w.x >> 16); tp[32] = (bf16_t)(w.y & 0xffff); tp[48] = (bf16_t)(w.y >> 16);
;                         tp[64] = (bf16_t)(w.z & 0xffff); tp[80] = (bf16_t)(w.z >> 16); tp[96] = (bf16_t)(w.w & 0xffff); tp[112] = (bf16_t)(w.w >> 16);
;                         asm volatile("s_waitcnt lgkmcnt(0)" ::: "memory");
;                         const u32x4 tv = *(const LAS u32x4*)(tw + (lane >> 1) * 32 + (lane & 1) * 16);
;                         asm volatile("s_waitcnt lgkmcnt(0)" ::: "memory");
;                         const int cc = (col - 8 * fq) - 2 * D + (lane >> 1), h = cc >> 6, d = cc & 63, t0 = (t - fr) + (lane & 1) * 8;
.LBB0_548:
	v_cvt_pk_bf16_f32 v8, v4, v5
	v_cvt_pk_bf16_f32 v9, v6, v7
	v_cvt_pk_bf16_f32 v10, v0, v1
	v_cvt_pk_bf16_f32 v11, v2, v3
	s_and_b64 vcc, exec, s[40:41]
	s_mov_b64 s[4:5], -1
	s_cbranch_vccnz .LBB0_559
	s_and_b64 vcc, exec, s[38:39]
	s_cbranch_vccnz .LBB0_555
	v_cndmask_b32_e64 v13, v33, v35, s[0:1]
	v_cndmask_b32_e64 v12, v32, v34, s[0:1]
	v_lshl_add_u64 v[12:13], v[12:13], 2, s[28:29]
	v_mov_b32_e32 v155, v65
	v_lshl_add_u64 v[12:13], v[154:155], 2, v[12:13]
	v_add_co_u32_e32 v14, vcc, 0xffffe200, v12
	s_addk_i32 s26, 0xf880
	s_nop 0
	v_addc_co_u32_e32 v15, vcc, -1, v13, vcc
	v_add_co_u32_e32 v12, vcc, 0xffffe210, v12
	global_store_dwordx4 v[14:15], v[4:7], off
	s_nop 0
	v_addc_co_u32_e32 v13, vcc, -1, v13, vcc
	global_store_dwordx4 v[12:13], v[0:3], off
	ds_write_b16 v180, v8
	ds_write_b16_d16_hi v180, v8 offset:32
	ds_write_b16 v180, v9 offset:64
	ds_write_b16_d16_hi v180, v9 offset:96
	ds_write_b16 v180, v10 offset:128
	ds_write_b16_d16_hi v180, v10 offset:160
	ds_write_b16 v180, v11 offset:192
	ds_write_b16_d16_hi v180, v11 offset:224
	s_waitcnt lgkmcnt(0)
	v_add_u32_e32 v12, v181, v178
	ds_read_b128 v[12:15], v12
	s_waitcnt lgkmcnt(0)
	s_ashr_i32 s4, s26, 6
	v_add_u32_e32 v18, s4, v40
	v_ashrrev_i32_e32 v19, 31, v18
	s_and_saveexec_b64 s[4:5], s[42:43]
	s_xor_b64 s[4:5], exec, s[4:5]
	v_lshlrev_b64 v[16:17], 6, v[18:19]
	v_or_b32_e32 v16, v16, v146
	v_mov_b64_e32 v[18:19], s[52:53]
	s_movk_i32 s10, 0x1080
	v_mad_u64_u32 v[18:19], s[6:7], v16, s10, v[18:19]
	v_mad_i32_i24 v19, v17, s10, v19
	v_lshl_add_u64 v[16:17], v[18:19], 0, s[96:97]
	s_andn2_saveexec_b64 s[4:5], s[4:5]
	v_lshlrev_b64 v[16:17], 19, v[18:19]
	v_lshl_add_u64 v[16:17], v[148:149], 0, v[16:17]
	s_or_b64 exec, exec, s[4:5]
	v_lshl_add_u64 v[16:17], v[64:65], 1, v[16:17]
	s_mov_b64 s[4:5], 0
	s_waitcnt lgkmcnt(0)
	global_store_dwordx4 v[16:17], v[12:15], off
.LBB0_555:
	s_and_b64 vcc, exec, s[4:5]
	s_cbranch_vccz .LBB0_557
	v_add_u32_e32 v12, 0xfffffc80, v154
	v_cndmask_b32_e64 v15, v29, v31, s[0:1]
	v_cndmask_b32_e64 v14, v28, v30, s[0:1]
	v_lshl_add_u64 v[14:15], v[14:15], 2, s[28:29]
	v_ashrrev_i32_e32 v13, 31, v12
	v_lshl_add_u64 v[14:15], v[12:13], 2, v[14:15]
	global_store_dwordx4 v[14:15], v[4:7], off
	global_store_dwordx4 v[14:15], v[0:3], off offset:16
	s_nop 1
	v_lshl_add_u64 v[0:1], s[50:51], 0, v[24:25]
	v_lshl_add_u64 v[2:3], s[48:49], 0, v[26:27]
	v_cndmask_b32_e64 v1, v1, v3, s[0:1]
	v_cndmask_b32_e64 v0, v0, v2, s[0:1]
	v_lshl_add_u64 v[0:1], v[12:13], 1, v[0:1]
	global_store_dwordx4 v[0:1], v[8:11], off

; DI unsigned pk2(float lo, float hi) { f32x2 v = {lo, hi}; bf16x2_t b = __builtin_convertvector(v, bf16x2_t); return __builtin_bit_cast(unsigned, b); }
;     DI void operator()(const f32x4 (&acc)[2][2][4][2], const Unit& u, int wr, int wc, int fr, int fq) const {
;     ...
;                 for (int bj = 0; bj < 2; ++bj) {
;                     const int col = u.pn * 256 + bj * 128 + wc * 32 + 8 * fq;
;                     u32x4 w; w.x = pk2(acc[ai][bj][m][0][0], acc[ai][bj][m][0][1]); w.y = pk2(acc[ai][bj][m][0][2], acc[ai][bj][m][0][3]); w.z = pk2(acc[ai][bj][m][1][0], acc[ai][bj][m][1][1]); w.w = pk2(acc[ai][bj][m][1][2], acc[ai][bj][m][1][3]);
;                     if (u.pn < 12) {
;                         *(u32x4*)(PRE + (size_t)row * DNQ + col) = w;
;                         if ((t & 63) >= 61) *(u32x4*)(HALO + ((size_t)(row >> 6) * 3 + ((t & 63) - 61)) * DNQ + col) = w;
;                         if (t >= L - 3) { float* o = out + (s ? O_DNCS : O_DNCP) + ((size_t)b * 3 + (t - (L - 3))) * DNQ + col; *(f32x4*)o = acc[ai][bj][m][0]; *(f32x4*)(o + 4) = acc[ai][bj][m][1]; }
;                     } else if (u.pn < 16) {
;                         __builtin_nontemporal_store(w, (u32x4*)(Z + (size_t)row * D + (col - DNQ)));
.LBB0_1141:
	s_andn2_b64 vcc, exec, s[12:13]
	s_cbranch_vccnz .LBB0_1143
	v_lshl_add_u64 v[156:157], s[34:35], 0, v[152:153]
	v_mov_b32_e32 v151, v65
	v_lshl_add_u64 v[156:157], v[150:151], 1, v[156:157]
	v_add_co_u32_e32 v156, vcc, 0xffffe800, v156
	s_nop 1
	v_addc_co_u32_e32 v157, vcc, -1, v157, vcc
	global_store_dwordx4 v[156:157], v[130:133], off

; DI unsigned pk2(float lo, float hi) { f32x2 v = {lo, hi}; bf16x2_t b = __builtin_convertvector(v, bf16x2_t); return __builtin_bit_cast(unsigned, b); }
;     DI void operator()(const f32x4 (&acc)[2][2][4][2], const Unit& u, int wr, int wc, int fr, int fq) const {
;     ...
;                 for (int bj = 0; bj < 2; ++bj) {
;                     const int col = u.pn * 256 + bj * 128 + wc * 32 + 8 * fq;
;                     u32x4 w; w.x = pk2(acc[ai][bj][m][0][0], acc[ai][bj][m][0][1]); w.y = pk2(acc[ai][bj][m][0][2], acc[ai][bj][m][0][3]); w.z = pk2(acc[ai][bj][m][1][0], acc[ai][bj][m][1][1]); w.w = pk2(acc[ai][bj][m][1][2], acc[ai][bj][m][1][3]);
;                     if (u.pn < 12) {
;                         *(u32x4*)(PRE + (size_t)row * DNQ + col) = w;
;                         if ((t & 63) >= 61) *(u32x4*)(HALO + ((size_t)(row >> 6) * 3 + ((t & 63) - 61)) * DNQ + col) = w;
;                         if (t >= L - 3) { float* o = out + (s ? O_DNCS : O_DNCP) + ((size_t)b * 3 + (t - (L - 3))) * DNQ + col; *(f32x4*)o = acc[ai][bj][m][0]; *(f32x4*)(o + 4) = acc[ai][bj][m][1]; }
;                     } else if (u.pn < 16) {
;                         __builtin_nontemporal_store(w, (u32x4*)(Z + (size_t)row * D + (col - DNQ)));
.LBB0_1148:
	v_cndmask_b32_e64 v64, 0, 1, s[6:7]
	v_cmp_ne_u32_e64 s[42:43], 1, v64
	v_cndmask_b32_e64 v64, 0, 1, s[10:11]
	v_cvt_pk_bf16_f32 v122, v118, v119
	v_cvt_pk_bf16_f32 v123, v120, v121
	v_cvt_pk_bf16_f32 v124, v114, v115
	v_cvt_pk_bf16_f32 v125, v116, v117
	s_mov_b64 s[0:1], -1
	s_andn2_b64 vcc, exec, s[6:7]
	v_cmp_ne_u32_e64 s[40:41], 1, v64
	s_cbranch_vccnz .LBB0_1152
	s_and_b64 vcc, exec, s[40:41]
	s_cbranch_vccnz .LBB0_1151
	v_lshl_add_u64 v[126:127], s[34:35], 0, v[152:153]
	v_mov_b32_e32 v64, v150
	v_lshl_add_u64 v[126:127], v[64:65], 1, v[126:127]
	v_add_co_u32_e32 v126, vcc, 0xffffe900, v126
	s_nop 1
	v_addc_co_u32_e32 v127, vcc, -1, v127, vcc
	global_store_dwordx4 v[126:127], v[122:125], off

; DI unsigned pk2(float lo, float hi) { f32x2 v = {lo, hi}; bf16x2_t b = __builtin_convertvector(v, bf16x2_t); return __builtin_bit_cast(unsigned, b); }
;     DI void operator()(const f32x4 (&acc)[2][2][4][2], const Unit& u, int wr, int wc, int fr, int fq) const {
;     ...
;                 for (int bj = 0; bj < 2; ++bj) {
;                     const int col = u.pn * 256 + bj * 128 + wc * 32 + 8 * fq;
;                     u32x4 w; w.x = pk2(acc[ai][bj][m][0][0], acc[ai][bj][m][0][1]); w.y = pk2(acc[ai][bj][m][0][2], acc[ai][bj][m][0][3]); w.z = pk2(acc[ai][bj][m][1][0], acc[ai][bj][m][1][1]); w.w = pk2(acc[ai][bj][m][1][2], acc[ai][bj][m][1][3]);
;                     if (u.pn < 12) {
;                         *(u32x4*)(PRE + (size_t)row * DNQ + col) = w;
;                         if ((t & 63) >= 61) *(u32x4*)(HALO + ((size_t)(row >> 6) * 3 + ((t & 63) - 61)) * DNQ + col) = w;
;                         if (t >= L - 3) { float* o = out + (s ? O_DNCS : O_DNCP) + ((size_t)b * 3 + (t - (L - 3))) * DNQ + col; *(f32x4*)o = acc[ai][bj][m][0]; *(f32x4*)(o + 4) = acc[ai][bj][m][1]; }
;                     } else if (u.pn < 16) {
;                         __builtin_nontemporal_store(w, (u32x4*)(Z + (size_t)row * D + (col - DNQ)));
.LBB0_1161:
	s_andn2_b64 vcc, exec, s[4:5]
	s_cbranch_vccnz .LBB0_1163
	v_lshl_add_u64 v[122:123], s[34:35], 0, v[118:119]
	v_mov_b32_e32 v64, v150
	v_lshl_add_u64 v[122:123], v[64:65], 1, v[122:123]
	v_add_co_u32_e32 v122, vcc, 0xffffe800, v122
	s_nop 1
	v_addc_co_u32_e32 v123, vcc, -1, v123, vcc
	global_store_dwordx4 v[122:123], v[114:117], off

; DI unsigned pk2(float lo, float hi) { f32x2 v = {lo, hi}; bf16x2_t b = __builtin_convertvector(v, bf16x2_t); return __builtin_bit_cast(unsigned, b); }
;     DI void operator()(const f32x4 (&acc)[2][2][4][2], const Unit& u, int wr, int wc, int fr, int fq) const {
;     ...
;                 for (int bj = 0; bj < 2; ++bj) {
;                     const int col = u.pn * 256 + bj * 128 + wc * 32 + 8 * fq;
;                     u32x4 w; w.x = pk2(acc[ai][bj][m][0][0], acc[ai][bj][m][0][1]); w.y = pk2(acc[ai][bj][m][0][2], acc[ai][bj][m][0][3]); w.z = pk2(acc[ai][bj][m][1][0], acc[ai][bj][m][1][1]); w.w = pk2(acc[ai][bj][m][1][2], acc[ai][bj][m][1][3]);
;                     if (u.pn < 12) {
;                         *(u32x4*)(PRE + (size_t)row * DNQ + col) = w;
;                         if ((t & 63) >= 61) *(u32x4*)(HALO + ((size_t)(row >> 6) * 3 + ((t & 63) - 61)) * DNQ + col) = w;
;                         if (t >= L - 3) { float* o = out + (s ? O_DNCS : O_DNCP) + ((size_t)b * 3 + (t - (L - 3))) * DNQ + col; *(f32x4*)o = acc[ai][bj][m][0]; *(f32x4*)(o + 4) = acc[ai][bj][m][1]; }
;                     } else if (u.pn < 16) {
;                         __builtin_nontemporal_store(w, (u32x4*)(Z + (size_t)row * D + (col - DNQ)));
.LBB0_1168:
	s_nop 0
	v_cvt_pk_bf16_f32 v106, v102, v103
	v_cvt_pk_bf16_f32 v107, v104, v105
	v_cvt_pk_bf16_f32 v108, v98, v99
	v_cvt_pk_bf16_f32 v109, v100, v101
	s_and_b64 vcc, exec, s[42:43]
	s_mov_b64 s[0:1], -1
	s_cbranch_vccnz .LBB0_1172
	s_and_b64 vcc, exec, s[40:41]
	s_cbranch_vccnz .LBB0_1171
	v_lshl_add_u64 v[110:111], s[34:35], 0, v[118:119]
	v_mov_b32_e32 v64, v150
	v_lshl_add_u64 v[110:111], v[64:65], 1, v[110:111]
	v_add_co_u32_e32 v110, vcc, 0xffffe900, v110
	s_nop 1
	v_addc_co_u32_e32 v111, vcc, -1, v111, vcc
	global_store_dwordx4 v[110:111], v[106:109], off

; DI unsigned pk2(float lo, float hi) { f32x2 v = {lo, hi}; bf16x2_t b = __builtin_convertvector(v, bf16x2_t); return __builtin_bit_cast(unsigned, b); }
;     DI void operator()(const f32x4 (&acc)[2][2][4][2], const Unit& u, int wr, int wc, int fr, int fq) const {
;     ...
;                 for (int bj = 0; bj < 2; ++bj) {
;                     const int col = u.pn * 256 + bj * 128 + wc * 32 + 8 * fq;
;                     u32x4 w; w.x = pk2(acc[ai][bj][m][0][0], acc[ai][bj][m][0][1]); w.y = pk2(acc[ai][bj][m][0][2], acc[ai][bj][m][0][3]); w.z = pk2(acc[ai][bj][m][1][0], acc[ai][bj][m][1][1]); w.w = pk2(acc[ai][bj][m][1][2], acc[ai][bj][m][1][3]);
;                     if (u.pn < 12) {
;                         *(u32x4*)(PRE + (size_t)row * DNQ + col) = w;
;                         if ((t & 63) >= 61) *(u32x4*)(HALO + ((size_t)(row >> 6) * 3 + ((t & 63) - 61)) * DNQ + col) = w;
;                         if (t >= L - 3) { float* o = out + (s ? O_DNCS : O_DNCP) + ((size_t)b * 3 + (t - (L - 3))) * DNQ + col; *(f32x4*)o = acc[ai][bj][m][0]; *(f32x4*)(o + 4) = acc[ai][bj][m][1]; }
;                     } else if (u.pn < 16) {
;                         __builtin_nontemporal_store(w, (u32x4*)(Z + (size_t)row * D + (col - DNQ)));
.LBB0_1181:
	s_andn2_b64 vcc, exec, s[4:5]
	s_cbranch_vccnz .LBB0_1183
	v_lshl_add_u64 v[106:107], s[34:35], 0, v[102:103]
	v_mov_b32_e32 v64, v150
	v_lshl_add_u64 v[106:107], v[64:65], 1, v[106:107]
	v_add_co_u32_e32 v106, vcc, 0xffffe800, v106
	s_nop 1
	v_addc_co_u32_e32 v107, vcc, -1, v107, vcc
	global_store_dwordx4 v[106:107], v[98:101], off

; DI unsigned pk2(float lo, float hi) { f32x2 v = {lo, hi}; bf16x2_t b = __builtin_convertvector(v, bf16x2_t); return __builtin_bit_cast(unsigned, b); }
;     DI void operator()(const f32x4 (&acc)[2][2][4][2], const Unit& u, int wr, int wc, int fr, int fq) const {
;     ...
;                 for (int bj = 0; bj < 2; ++bj) {
;                     const int col = u.pn * 256 + bj * 128 + wc * 32 + 8 * fq;
;                     u32x4 w; w.x = pk2(acc[ai][bj][m][0][0], acc[ai][bj][m][0][1]); w.y = pk2(acc[ai][bj][m][0][2], acc[ai][bj][m][0][3]); w.z = pk2(acc[ai][bj][m][1][0], acc[ai][bj][m][1][1]); w.w = pk2(acc[ai][bj][m][1][2], acc[ai][bj][m][1][3]);
;                     if (u.pn < 12) {
;                         *(u32x4*)(PRE + (size_t)row * DNQ + col) = w;
;                         if ((t & 63) >= 61) *(u32x4*)(HALO + ((size_t)(row >> 6) * 3 + ((t & 63) - 61)) * DNQ + col) = w;
;                         if (t >= L - 3) { float* o = out + (s ? O_DNCS : O_DNCP) + ((size_t)b * 3 + (t - (L - 3))) * DNQ + col; *(f32x4*)o = acc[ai][bj][m][0]; *(f32x4*)(o + 4) = acc[ai][bj][m][1]; }
;                     } else if (u.pn < 16) {
;                         __builtin_nontemporal_store(w, (u32x4*)(Z + (size_t)row * D + (col - DNQ)));
.LBB0_1188:
	s_nop 0
	v_cvt_pk_bf16_f32 v90, v86, v87
	v_cvt_pk_bf16_f32 v91, v88, v89
	v_cvt_pk_bf16_f32 v92, v82, v83
	v_cvt_pk_bf16_f32 v93, v84, v85
	s_and_b64 vcc, exec, s[42:43]
	s_mov_b64 s[0:1], -1
	s_cbranch_vccnz .LBB0_1192
	s_and_b64 vcc, exec, s[40:41]
	s_cbranch_vccnz .LBB0_1191
	v_lshl_add_u64 v[94:95], s[34:35], 0, v[102:103]
	v_mov_b32_e32 v64, v150
	v_lshl_add_u64 v[94:95], v[64:65], 1, v[94:95]
	v_add_co_u32_e32 v94, vcc, 0xffffe900, v94
	s_nop 1
	v_addc_co_u32_e32 v95, vcc, -1, v95, vcc
	global_store_dwordx4 v[94:95], v[90:93], off

; DI unsigned pk2(float lo, float hi) { f32x2 v = {lo, hi}; bf16x2_t b = __builtin_convertvector(v, bf16x2_t); return __builtin_bit_cast(unsigned, b); }
;     DI void operator()(const f32x4 (&acc)[2][2][4][2], const Unit& u, int wr, int wc, int fr, int fq) const {
;     ...
;                 for (int bj = 0; bj < 2; ++bj) {
;                     const int col = u.pn * 256 + bj * 128 + wc * 32 + 8 * fq;
;                     u32x4 w; w.x = pk2(acc[ai][bj][m][0][0], acc[ai][bj][m][0][1]); w.y = pk2(acc[ai][bj][m][0][2], acc[ai][bj][m][0][3]); w.z = pk2(acc[ai][bj][m][1][0], acc[ai][bj][m][1][1]); w.w = pk2(acc[ai][bj][m][1][2], acc[ai][bj][m][1][3]);
;                     if (u.pn < 12) {
;                         *(u32x4*)(PRE + (size_t)row * DNQ + col) = w;
;                         if ((t & 63) >= 61) *(u32x4*)(HALO + ((size_t)(row >> 6) * 3 + ((t & 63) - 61)) * DNQ + col) = w;
;                         if (t >= L - 3) { float* o = out + (s ? O_DNCS : O_DNCP) + ((size_t)b * 3 + (t - (L - 3))) * DNQ + col; *(f32x4*)o = acc[ai][bj][m][0]; *(f32x4*)(o + 4) = acc[ai][bj][m][1]; }
;                     } else if (u.pn < 16) {
;                         __builtin_nontemporal_store(w, (u32x4*)(Z + (size_t)row * D + (col - DNQ)));
.LBB0_1201:
	s_andn2_b64 vcc, exec, s[4:5]
	s_cbranch_vccnz .LBB0_1203
	v_lshl_add_u64 v[90:91], s[34:35], 0, v[86:87]
	v_mov_b32_e32 v64, v150
	v_lshl_add_u64 v[90:91], v[64:65], 1, v[90:91]
	v_add_co_u32_e32 v90, vcc, 0xffffe800, v90
	s_nop 1
	v_addc_co_u32_e32 v91, vcc, -1, v91, vcc
	global_store_dwordx4 v[90:91], v[82:85], off

; DI unsigned pk2(float lo, float hi) { f32x2 v = {lo, hi}; bf16x2_t b = __builtin_convertvector(v, bf16x2_t); return __builtin_bit_cast(unsigned, b); }
;     DI void operator()(const f32x4 (&acc)[2][2][4][2], const Unit& u, int wr, int wc, int fr, int fq) const {
;     ...
;                 for (int bj = 0; bj < 2; ++bj) {
;                     const int col = u.pn * 256 + bj * 128 + wc * 32 + 8 * fq;
;                     u32x4 w; w.x = pk2(acc[ai][bj][m][0][0], acc[ai][bj][m][0][1]); w.y = pk2(acc[ai][bj][m][0][2], acc[ai][bj][m][0][3]); w.z = pk2(acc[ai][bj][m][1][0], acc[ai][bj][m][1][1]); w.w = pk2(acc[ai][bj][m][1][2], acc[ai][bj][m][1][3]);
;                     if (u.pn < 12) {
;                         *(u32x4*)(PRE + (size_t)row * DNQ + col) = w;
;                         if ((t & 63) >= 61) *(u32x4*)(HALO + ((size_t)(row >> 6) * 3 + ((t & 63) - 61)) * DNQ + col) = w;
;                         if (t >= L - 3) { float* o = out + (s ? O_DNCS : O_DNCP) + ((size_t)b * 3 + (t - (L - 3))) * DNQ + col; *(f32x4*)o = acc[ai][bj][m][0]; *(f32x4*)(o + 4) = acc[ai][bj][m][1]; }
;                     } else if (u.pn < 16) {
;                         __builtin_nontemporal_store(w, (u32x4*)(Z + (size_t)row * D + (col - DNQ)));
.LBB0_1210:
	s_nop 0
	v_cvt_pk_bf16_f32 v74, v70, v71
	v_cvt_pk_bf16_f32 v75, v72, v73
	v_cvt_pk_bf16_f32 v76, v66, v67
	v_cvt_pk_bf16_f32 v77, v68, v69
	s_and_b64 vcc, exec, s[42:43]
	s_mov_b64 s[0:1], -1
	s_cbranch_vccnz .LBB0_1214
	s_and_b64 vcc, exec, s[40:41]
	s_cbranch_vccnz .LBB0_1213
	v_lshl_add_u64 v[78:79], s[34:35], 0, v[86:87]
	v_mov_b32_e32 v64, v150
	v_lshl_add_u64 v[78:79], v[64:65], 1, v[78:79]
	v_add_co_u32_e32 v78, vcc, 0xffffe900, v78
	s_nop 1
	v_addc_co_u32_e32 v79, vcc, -1, v79, vcc
	global_store_dwordx4 v[78:79], v[74:77], off

; DI unsigned pk2(float lo, float hi) { f32x2 v = {lo, hi}; bf16x2_t b = __builtin_convertvector(v, bf16x2_t); return __builtin_bit_cast(unsigned, b); }
;     DI void operator()(const f32x4 (&acc)[2][2][4][2], const Unit& u, int wr, int wc, int fr, int fq) const {
;     ...
;                 for (int bj = 0; bj < 2; ++bj) {
;                     const int col = u.pn * 256 + bj * 128 + wc * 32 + 8 * fq;
;                     u32x4 w; w.x = pk2(acc[ai][bj][m][0][0], acc[ai][bj][m][0][1]); w.y = pk2(acc[ai][bj][m][0][2], acc[ai][bj][m][0][3]); w.z = pk2(acc[ai][bj][m][1][0], acc[ai][bj][m][1][1]); w.w = pk2(acc[ai][bj][m][1][2], acc[ai][bj][m][1][3]);
;                     if (u.pn < 12) {
;                         *(u32x4*)(PRE + (size_t)row * DNQ + col) = w;
;                         if ((t & 63) >= 61) *(u32x4*)(HALO + ((size_t)(row >> 6) * 3 + ((t & 63) - 61)) * DNQ + col) = w;
;                         if (t >= L - 3) { float* o = out + (s ? O_DNCS : O_DNCP) + ((size_t)b * 3 + (t - (L - 3))) * DNQ + col; *(f32x4*)o = acc[ai][bj][m][0]; *(f32x4*)(o + 4) = acc[ai][bj][m][1]; }
;                     } else if (u.pn < 16) {
;                         __builtin_nontemporal_store(w, (u32x4*)(Z + (size_t)row * D + (col - DNQ)));
.LBB0_1225:
	s_andn2_b64 vcc, exec, s[4:5]
	s_cbranch_vccnz .LBB0_1227
	v_lshl_add_u64 v[74:75], s[34:35], 0, v[70:71]
	v_mov_b32_e32 v64, v150
	v_lshl_add_u64 v[74:75], v[64:65], 1, v[74:75]
	v_add_co_u32_e32 v74, vcc, 0xffffe800, v74
	s_nop 1
	v_addc_co_u32_e32 v75, vcc, -1, v75, vcc
	global_store_dwordx4 v[74:75], v[66:69], off

; DI unsigned pk2(float lo, float hi) { f32x2 v = {lo, hi}; bf16x2_t b = __builtin_convertvector(v, bf16x2_t); return __builtin_bit_cast(unsigned, b); }
;     DI void operator()(const f32x4 (&acc)[2][2][4][2], const Unit& u, int wr, int wc, int fr, int fq) const {
;     ...
;                 for (int bj = 0; bj < 2; ++bj) {
;                     const int col = u.pn * 256 + bj * 128 + wc * 32 + 8 * fq;
;                     u32x4 w; w.x = pk2(acc[ai][bj][m][0][0], acc[ai][bj][m][0][1]); w.y = pk2(acc[ai][bj][m][0][2], acc[ai][bj][m][0][3]); w.z = pk2(acc[ai][bj][m][1][0], acc[ai][bj][m][1][1]); w.w = pk2(acc[ai][bj][m][1][2], acc[ai][bj][m][1][3]);
;                     if (u.pn < 12) {
;                         *(u32x4*)(PRE + (size_t)row * DNQ + col) = w;
;                         if ((t & 63) >= 61) *(u32x4*)(HALO + ((size_t)(row >> 6) * 3 + ((t & 63) - 61)) * DNQ + col) = w;
;                         if (t >= L - 3) { float* o = out + (s ? O_DNCS : O_DNCP) + ((size_t)b * 3 + (t - (L - 3))) * DNQ + col; *(f32x4*)o = acc[ai][bj][m][0]; *(f32x4*)(o + 4) = acc[ai][bj][m][1]; }
;                     } else if (u.pn < 16) {
;                         __builtin_nontemporal_store(w, (u32x4*)(Z + (size_t)row * D + (col - DNQ)));
.LBB0_1232:
	s_nop 0
	v_cvt_pk_bf16_f32 v56, v52, v53
	v_cvt_pk_bf16_f32 v57, v54, v55
	v_cvt_pk_bf16_f32 v58, v48, v49
	v_cvt_pk_bf16_f32 v59, v50, v51
	s_and_b64 vcc, exec, s[42:43]
	s_mov_b64 s[0:1], -1
	s_cbranch_vccnz .LBB0_1236
	s_and_b64 vcc, exec, s[40:41]
	s_cbranch_vccnz .LBB0_1235
	v_lshl_add_u64 v[60:61], s[34:35], 0, v[70:71]
	v_mov_b32_e32 v64, v150
	v_lshl_add_u64 v[60:61], v[64:65], 1, v[60:61]
	v_add_co_u32_e32 v60, vcc, 0xffffe900, v60
	s_nop 1
	v_addc_co_u32_e32 v61, vcc, -1, v61, vcc
	global_store_dwordx4 v[60:61], v[56:59], off

; DI unsigned pk2(float lo, float hi) { f32x2 v = {lo, hi}; bf16x2_t b = __builtin_convertvector(v, bf16x2_t); return __builtin_bit_cast(unsigned, b); }
;     DI void operator()(const f32x4 (&acc)[2][2][4][2], const Unit& u, int wr, int wc, int fr, int fq) const {
;     ...
;                 for (int bj = 0; bj < 2; ++bj) {
;                     const int col = u.pn * 256 + bj * 128 + wc * 32 + 8 * fq;
;                     u32x4 w; w.x = pk2(acc[ai][bj][m][0][0], acc[ai][bj][m][0][1]); w.y = pk2(acc[ai][bj][m][0][2], acc[ai][bj][m][0][3]); w.z = pk2(acc[ai][bj][m][1][0], acc[ai][bj][m][1][1]); w.w = pk2(acc[ai][bj][m][1][2], acc[ai][bj][m][1][3]);
;                     if (u.pn < 12) {
;                         *(u32x4*)(PRE + (size_t)row * DNQ + col) = w;
;                         if ((t & 63) >= 61) *(u32x4*)(HALO + ((size_t)(row >> 6) * 3 + ((t & 63) - 61)) * DNQ + col) = w;
;                         if (t >= L - 3) { float* o = out + (s ? O_DNCS : O_DNCP) + ((size_t)b * 3 + (t - (L - 3))) * DNQ + col; *(f32x4*)o = acc[ai][bj][m][0]; *(f32x4*)(o + 4) = acc[ai][bj][m][1]; }
;                     } else if (u.pn < 16) {
;                         __builtin_nontemporal_store(w, (u32x4*)(Z + (size_t)row * D + (col - DNQ)));
.LBB0_1245:
	s_andn2_b64 vcc, exec, s[4:5]
	s_cbranch_vccnz .LBB0_1247
	v_lshl_add_u64 v[56:57], s[34:35], 0, v[52:53]
	v_mov_b32_e32 v64, v150
	v_lshl_add_u64 v[56:57], v[64:65], 1, v[56:57]
	v_add_co_u32_e32 v56, vcc, 0xffffe800, v56
	s_nop 1
	v_addc_co_u32_e32 v57, vcc, -1, v57, vcc
	global_store_dwordx4 v[56:57], v[48:51], off

; DI unsigned pk2(float lo, float hi) { f32x2 v = {lo, hi}; bf16x2_t b = __builtin_convertvector(v, bf16x2_t); return __builtin_bit_cast(unsigned, b); }
;     DI void operator()(const f32x4 (&acc)[2][2][4][2], const Unit& u, int wr, int wc, int fr, int fq) const {
;     ...
;                 for (int bj = 0; bj < 2; ++bj) {
;                     const int col = u.pn * 256 + bj * 128 + wc * 32 + 8 * fq;
;                     u32x4 w; w.x = pk2(acc[ai][bj][m][0][0], acc[ai][bj][m][0][1]); w.y = pk2(acc[ai][bj][m][0][2], acc[ai][bj][m][0][3]); w.z = pk2(acc[ai][bj][m][1][0], acc[ai][bj][m][1][1]); w.w = pk2(acc[ai][bj][m][1][2], acc[ai][bj][m][1][3]);
;                     if (u.pn < 12) {
;                         *(u32x4*)(PRE + (size_t)row * DNQ + col) = w;
;                         if ((t & 63) >= 61) *(u32x4*)(HALO + ((size_t)(row >> 6) * 3 + ((t & 63) - 61)) * DNQ + col) = w;
;                         if (t >= L - 3) { float* o = out + (s ? O_DNCS : O_DNCP) + ((size_t)b * 3 + (t - (L - 3))) * DNQ + col; *(f32x4*)o = acc[ai][bj][m][0]; *(f32x4*)(o + 4) = acc[ai][bj][m][1]; }
;                     } else if (u.pn < 16) {
;                         __builtin_nontemporal_store(w, (u32x4*)(Z + (size_t)row * D + (col - DNQ)));
.LBB0_1252:
	s_nop 0
	v_cvt_pk_bf16_f32 v40, v36, v37
	v_cvt_pk_bf16_f32 v41, v38, v39
	v_cvt_pk_bf16_f32 v42, v32, v33
	v_cvt_pk_bf16_f32 v43, v34, v35
	s_and_b64 vcc, exec, s[42:43]
	s_mov_b64 s[0:1], -1
	s_cbranch_vccnz .LBB0_1256
	s_and_b64 vcc, exec, s[40:41]
	s_cbranch_vccnz .LBB0_1255
	v_lshl_add_u64 v[44:45], s[34:35], 0, v[52:53]
	v_mov_b32_e32 v64, v150
	v_lshl_add_u64 v[44:45], v[64:65], 1, v[44:45]
	v_add_co_u32_e32 v44, vcc, 0xffffe900, v44
	s_nop 1
	v_addc_co_u32_e32 v45, vcc, -1, v45, vcc
	global_store_dwordx4 v[44:45], v[40:43], off

; DI unsigned pk2(float lo, float hi) { f32x2 v = {lo, hi}; bf16x2_t b = __builtin_convertvector(v, bf16x2_t); return __builtin_bit_cast(unsigned, b); }
;     DI void operator()(const f32x4 (&acc)[2][2][4][2], const Unit& u, int wr, int wc, int fr, int fq) const {
;     ...
;                 for (int bj = 0; bj < 2; ++bj) {
;                     const int col = u.pn * 256 + bj * 128 + wc * 32 + 8 * fq;
;                     u32x4 w; w.x = pk2(acc[ai][bj][m][0][0], acc[ai][bj][m][0][1]); w.y = pk2(acc[ai][bj][m][0][2], acc[ai][bj][m][0][3]); w.z = pk2(acc[ai][bj][m][1][0], acc[ai][bj][m][1][1]); w.w = pk2(acc[ai][bj][m][1][2], acc[ai][bj][m][1][3]);
;                     if (u.pn < 12) {
;                         *(u32x4*)(PRE + (size_t)row * DNQ + col) = w;
;                         if ((t & 63) >= 61) *(u32x4*)(HALO + ((size_t)(row >> 6) * 3 + ((t & 63) - 61)) * DNQ + col) = w;
;                         if (t >= L - 3) { float* o = out + (s ? O_DNCS : O_DNCP) + ((size_t)b * 3 + (t - (L - 3))) * DNQ + col; *(f32x4*)o = acc[ai][bj][m][0]; *(f32x4*)(o + 4) = acc[ai][bj][m][1]; }
;                     } else if (u.pn < 16) {
;                         __builtin_nontemporal_store(w, (u32x4*)(Z + (size_t)row * D + (col - DNQ)));
.LBB0_1265:
	s_andn2_b64 vcc, exec, s[4:5]
	s_cbranch_vccnz .LBB0_1267
	v_lshl_add_u64 v[40:41], s[34:35], 0, v[36:37]
	v_mov_b32_e32 v64, v150
	v_lshl_add_u64 v[40:41], v[64:65], 1, v[40:41]
	v_add_co_u32_e32 v40, vcc, 0xffffe800, v40
	s_nop 1
	v_addc_co_u32_e32 v41, vcc, -1, v41, vcc
	global_store_dwordx4 v[40:41], v[32:35], off

; DI unsigned pk2(float lo, float hi) { f32x2 v = {lo, hi}; bf16x2_t b = __builtin_convertvector(v, bf16x2_t); return __builtin_bit_cast(unsigned, b); }
;     DI void operator()(const f32x4 (&acc)[2][2][4][2], const Unit& u, int wr, int wc, int fr, int fq) const {
;     ...
;                 for (int bj = 0; bj < 2; ++bj) {
;                     const int col = u.pn * 256 + bj * 128 + wc * 32 + 8 * fq;
;                     u32x4 w; w.x = pk2(acc[ai][bj][m][0][0], acc[ai][bj][m][0][1]); w.y = pk2(acc[ai][bj][m][0][2], acc[ai][bj][m][0][3]); w.z = pk2(acc[ai][bj][m][1][0], acc[ai][bj][m][1][1]); w.w = pk2(acc[ai][bj][m][1][2], acc[ai][bj][m][1][3]);
;                     if (u.pn < 12) {
;                         *(u32x4*)(PRE + (size_t)row * DNQ + col) = w;
;                         if ((t & 63) >= 61) *(u32x4*)(HALO + ((size_t)(row >> 6) * 3 + ((t & 63) - 61)) * DNQ + col) = w;
;                         if (t >= L - 3) { float* o = out + (s ? O_DNCS : O_DNCP) + ((size_t)b * 3 + (t - (L - 3))) * DNQ + col; *(f32x4*)o = acc[ai][bj][m][0]; *(f32x4*)(o + 4) = acc[ai][bj][m][1]; }
;                     } else if (u.pn < 16) {
;                         __builtin_nontemporal_store(w, (u32x4*)(Z + (size_t)row * D + (col - DNQ)));
.LBB0_1272:
	s_nop 0
	v_cvt_pk_bf16_f32 v24, v20, v21
	v_cvt_pk_bf16_f32 v25, v22, v23
	v_cvt_pk_bf16_f32 v26, v16, v17
	v_cvt_pk_bf16_f32 v27, v18, v19
	s_and_b64 vcc, exec, s[42:43]
	s_mov_b64 s[0:1], -1
	s_cbranch_vccnz .LBB0_1276
	s_and_b64 vcc, exec, s[40:41]
	s_cbranch_vccnz .LBB0_1275
	v_lshl_add_u64 v[28:29], s[34:35], 0, v[36:37]
	v_mov_b32_e32 v64, v150
	v_lshl_add_u64 v[28:29], v[64:65], 1, v[28:29]
	v_add_co_u32_e32 v28, vcc, 0xffffe900, v28
	s_nop 1
	v_addc_co_u32_e32 v29, vcc, -1, v29, vcc
	global_store_dwordx4 v[28:29], v[24:27], off

; DI unsigned pk2(float lo, float hi) { f32x2 v = {lo, hi}; bf16x2_t b = __builtin_convertvector(v, bf16x2_t); return __builtin_bit_cast(unsigned, b); }
;     DI void operator()(const f32x4 (&acc)[2][2][4][2], const Unit& u, int wr, int wc, int fr, int fq) const {
;     ...
;                 for (int bj = 0; bj < 2; ++bj) {
;                     const int col = u.pn * 256 + bj * 128 + wc * 32 + 8 * fq;
;                     u32x4 w; w.x = pk2(acc[ai][bj][m][0][0], acc[ai][bj][m][0][1]); w.y = pk2(acc[ai][bj][m][0][2], acc[ai][bj][m][0][3]); w.z = pk2(acc[ai][bj][m][1][0], acc[ai][bj][m][1][1]); w.w = pk2(acc[ai][bj][m][1][2], acc[ai][bj][m][1][3]);
;                     if (u.pn < 12) {
;                         *(u32x4*)(PRE + (size_t)row * DNQ + col) = w;
;                         if ((t & 63) >= 61) *(u32x4*)(HALO + ((size_t)(row >> 6) * 3 + ((t & 63) - 61)) * DNQ + col) = w;
;                         if (t >= L - 3) { float* o = out + (s ? O_DNCS : O_DNCP) + ((size_t)b * 3 + (t - (L - 3))) * DNQ + col; *(f32x4*)o = acc[ai][bj][m][0]; *(f32x4*)(o + 4) = acc[ai][bj][m][1]; }
;                     } else if (u.pn < 16) {
;                         __builtin_nontemporal_store(w, (u32x4*)(Z + (size_t)row * D + (col - DNQ)));
.LBB0_1285:
	s_andn2_b64 vcc, exec, s[4:5]
	s_cbranch_vccnz .LBB0_1287
	v_lshl_add_u64 v[24:25], s[34:35], 0, v[20:21]
	v_mov_b32_e32 v64, v150
	v_lshl_add_u64 v[24:25], v[64:65], 1, v[24:25]
	v_add_co_u32_e32 v24, vcc, 0xffffe800, v24
	s_nop 1
	v_addc_co_u32_e32 v25, vcc, -1, v25, vcc
	global_store_dwordx4 v[24:25], v[16:19], off

; DI unsigned pk2(float lo, float hi) { f32x2 v = {lo, hi}; bf16x2_t b = __builtin_convertvector(v, bf16x2_t); return __builtin_bit_cast(unsigned, b); }
;     DI void operator()(const f32x4 (&acc)[2][2][4][2], const Unit& u, int wr, int wc, int fr, int fq) const {
;     ...
;                 for (int bj = 0; bj < 2; ++bj) {
;                     const int col = u.pn * 256 + bj * 128 + wc * 32 + 8 * fq;
;                     u32x4 w; w.x = pk2(acc[ai][bj][m][0][0], acc[ai][bj][m][0][1]); w.y = pk2(acc[ai][bj][m][0][2], acc[ai][bj][m][0][3]); w.z = pk2(acc[ai][bj][m][1][0], acc[ai][bj][m][1][1]); w.w = pk2(acc[ai][bj][m][1][2], acc[ai][bj][m][1][3]);
;                     if (u.pn < 12) {
;                         *(u32x4*)(PRE + (size_t)row * DNQ + col) = w;
;                         if ((t & 63) >= 61) *(u32x4*)(HALO + ((size_t)(row >> 6) * 3 + ((t & 63) - 61)) * DNQ + col) = w;
;                         if (t >= L - 3) { float* o = out + (s ? O_DNCS : O_DNCP) + ((size_t)b * 3 + (t - (L - 3))) * DNQ + col; *(f32x4*)o = acc[ai][bj][m][0]; *(f32x4*)(o + 4) = acc[ai][bj][m][1]; }
;                     } else if (u.pn < 16) {
;                         __builtin_nontemporal_store(w, (u32x4*)(Z + (size_t)row * D + (col - DNQ)));
.LBB0_1294:
	s_nop 0
	v_cvt_pk_bf16_f32 v8, v4, v5
	v_cvt_pk_bf16_f32 v9, v6, v7
	v_cvt_pk_bf16_f32 v10, v0, v1
	v_cvt_pk_bf16_f32 v11, v2, v3
	s_and_b64 vcc, exec, s[42:43]
	s_mov_b64 s[0:1], -1
	s_cbranch_vccnz .LBB0_1299
	s_and_b64 vcc, exec, s[40:41]
	s_cbranch_vccnz .LBB0_1297
	v_lshl_add_u64 v[12:13], s[34:35], 0, v[20:21]
	v_mov_b32_e32 v64, v150
	v_lshl_add_u64 v[12:13], v[64:65], 1, v[12:13]
	v_add_co_u32_e32 v12, vcc, 0xffffe900, v12
	s_nop 1
	v_addc_co_u32_e32 v13, vcc, -1, v13, vcc
	global_store_dwordx4 v[12:13], v[8:11], off
